# nt hint also on the read-once f32 weight loads of the bf16 weight-copy items (P0 and the late copies in P4)
# speedup vs baseline: 1.0359x; 1.0175x over previous
.LBB0_15:
	s_cmpk_gt_i32 s29, 0x5ff
	s_mov_b64 s[2:3], -1
	s_cbranch_scc0 .LBB0_93
	s_cmpk_gt_u32 s29, 0x7ff
	s_cbranch_scc0 .LBB0_90
	s_cmpk_gt_u32 s29, 0xfff
	s_cbranch_scc0 .LBB0_23
	s_cmpk_gt_u32 s29, 0x17ff
	s_cbranch_scc0 .LBB0_20
	s_add_i32 s0, s29, 0xe800
	s_and_b32 s2, s0, 0xffff
	s_mul_i32 s2, s2, 0xaaab
	s_lshr_b32 s2, s2, 21
	s_mul_i32 s3, s2, 48
	s_sub_i32 s0, s0, s3
	s_and_b32 s3, s0, 0xffff
	s_lshl_b32 s0, s3, 7
	v_lshl_or_b32 v0, s2, 6, v28
	v_lshl_add_u64 v[22:23], v[12:13], 0, s[0:1]
	v_mad_u64_u32 v[24:25], s[4:5], v0, s27, v[22:23]
	global_load_dword v26, v[24:25], off nt
	v_lshlrev_b32_e32 v24, 2, v0
	v_or_b32_e32 v73, 2, v0
	global_load_dword v27, v24, s[12:13]
	v_mad_u64_u32 v[24:25], s[4:5], v73, s27, v[22:23]
	global_load_dword v74, v[24:25], off nt
	v_lshlrev_b32_e32 v24, 2, v73
	v_or_b32_e32 v75, 4, v0
	global_load_dword v73, v24, s[12:13]
	v_mad_u64_u32 v[24:25], s[4:5], v75, s27, v[22:23]
	global_load_dword v76, v[24:25], off nt
	v_lshlrev_b32_e32 v24, 2, v75
	v_or_b32_e32 v77, 6, v0
	global_load_dword v75, v24, s[12:13]
	v_mad_u64_u32 v[24:25], s[4:5], v77, s27, v[22:23]
	global_load_dword v78, v[24:25], off nt
	v_lshlrev_b32_e32 v24, 2, v77
	v_or_b32_e32 v79, 8, v0
	global_load_dword v77, v24, s[12:13]
	v_mad_u64_u32 v[24:25], s[4:5], v79, s27, v[22:23]
	global_load_dword v80, v[24:25], off nt
	v_lshlrev_b32_e32 v24, 2, v79
	v_or_b32_e32 v81, 10, v0
	global_load_dword v79, v24, s[12:13]
	v_mad_u64_u32 v[24:25], s[4:5], v81, s27, v[22:23]
	global_load_dword v82, v[24:25], off nt
	v_lshlrev_b32_e32 v24, 2, v81
	v_or_b32_e32 v83, 12, v0
	global_load_dword v81, v24, s[12:13]
	v_mad_u64_u32 v[24:25], s[4:5], v83, s27, v[22:23]
	global_load_dword v84, v[24:25], off nt
	v_lshlrev_b32_e32 v24, 2, v83
	v_or_b32_e32 v85, 14, v0
	global_load_dword v83, v24, s[12:13]
	v_mad_u64_u32 v[24:25], s[4:5], v85, s27, v[22:23]
	global_load_dword v86, v[24:25], off nt
	v_lshlrev_b32_e32 v24, 2, v85
	v_or_b32_e32 v87, 16, v0
	global_load_dword v85, v24, s[12:13]
	v_mad_u64_u32 v[24:25], s[4:5], v87, s27, v[22:23]
	global_load_dword v88, v[24:25], off nt
	v_lshlrev_b32_e32 v24, 2, v87
	v_or_b32_e32 v89, 18, v0
	global_load_dword v87, v24, s[12:13]
	v_mad_u64_u32 v[24:25], s[4:5], v89, s27, v[22:23]
	global_load_dword v90, v[24:25], off nt
	v_lshlrev_b32_e32 v24, 2, v89
	v_or_b32_e32 v91, 20, v0
	global_load_dword v89, v24, s[12:13]
	v_mad_u64_u32 v[24:25], s[4:5], v91, s27, v[22:23]
	global_load_dword v92, v[24:25], off nt
	v_lshlrev_b32_e32 v24, 2, v91
	v_or_b32_e32 v93, 22, v0
	global_load_dword v91, v24, s[12:13]
	v_mad_u64_u32 v[24:25], s[4:5], v93, s27, v[22:23]
	global_load_dword v94, v[24:25], off nt
	v_lshlrev_b32_e32 v24, 2, v93
	v_or_b32_e32 v95, 24, v0
	global_load_dword v93, v24, s[12:13]
	v_mad_u64_u32 v[24:25], s[4:5], v95, s27, v[22:23]
	global_load_dword v96, v[24:25], off nt
	v_lshlrev_b32_e32 v24, 2, v95
	v_or_b32_e32 v97, 26, v0
	global_load_dword v95, v24, s[12:13]
	v_mad_u64_u32 v[24:25], s[4:5], v97, s27, v[22:23]
	global_load_dword v98, v[24:25], off nt
	v_lshlrev_b32_e32 v24, 2, v97
	v_or_b32_e32 v99, 28, v0
	global_load_dword v97, v24, s[12:13]
	v_mad_u64_u32 v[24:25], s[4:5], v99, s27, v[22:23]
	global_load_dword v100, v[24:25], off nt
	v_lshlrev_b32_e32 v24, 2, v99
	v_or_b32_e32 v101, 30, v0
	global_load_dword v99, v24, s[12:13]
	v_mad_u64_u32 v[24:25], s[4:5], v101, s27, v[22:23]
	global_load_dword v102, v[24:25], off nt
	v_lshlrev_b32_e32 v24, 2, v101
	v_or_b32_e32 v103, 32, v0
	global_load_dword v101, v24, s[12:13]
	v_mad_u64_u32 v[24:25], s[4:5], v103, s27, v[22:23]
	global_load_dword v104, v[24:25], off nt
	v_lshlrev_b32_e32 v24, 2, v103
	v_or_b32_e32 v105, 34, v0
	global_load_dword v103, v24, s[12:13]
	v_mad_u64_u32 v[24:25], s[4:5], v105, s27, v[22:23]
	global_load_dword v106, v[24:25], off nt
	v_lshlrev_b32_e32 v24, 2, v105
	v_or_b32_e32 v107, 36, v0
	global_load_dword v105, v24, s[12:13]
	v_mad_u64_u32 v[24:25], s[4:5], v107, s27, v[22:23]
	global_load_dword v108, v[24:25], off nt
	v_lshlrev_b32_e32 v24, 2, v107
	v_or_b32_e32 v109, 38, v0
	global_load_dword v107, v24, s[12:13]
	v_mad_u64_u32 v[24:25], s[4:5], v109, s27, v[22:23]
	global_load_dword v110, v[24:25], off nt
	v_lshlrev_b32_e32 v24, 2, v109
	v_or_b32_e32 v111, 40, v0
	global_load_dword v109, v24, s[12:13]
	v_mad_u64_u32 v[24:25], s[4:5], v111, s27, v[22:23]
	global_load_dword v112, v[24:25], off nt
	v_lshlrev_b32_e32 v24, 2, v111
	v_or_b32_e32 v113, 42, v0
	global_load_dword v111, v24, s[12:13]
	v_mad_u64_u32 v[24:25], s[4:5], v113, s27, v[22:23]
	global_load_dword v114, v[24:25], off nt
	v_lshlrev_b32_e32 v24, 2, v113
	v_or_b32_e32 v115, 44, v0
	global_load_dword v113, v24, s[12:13]
	v_mad_u64_u32 v[24:25], s[4:5], v115, s27, v[22:23]
	global_load_dword v116, v[24:25], off nt
	v_lshlrev_b32_e32 v24, 2, v115
	v_or_b32_e32 v117, 46, v0
	global_load_dword v115, v24, s[12:13]
	v_mad_u64_u32 v[24:25], s[4:5], v117, s27, v[22:23]
	global_load_dword v118, v[24:25], off nt
	v_lshlrev_b32_e32 v24, 2, v117
	v_or_b32_e32 v119, 48, v0
	global_load_dword v117, v24, s[12:13]
	v_mad_u64_u32 v[24:25], s[4:5], v119, s27, v[22:23]
	global_load_dword v120, v[24:25], off nt
	v_lshlrev_b32_e32 v24, 2, v119
	v_or_b32_e32 v121, 50, v0
	global_load_dword v119, v24, s[12:13]
	v_mad_u64_u32 v[24:25], s[4:5], v121, s27, v[22:23]
	global_load_dword v122, v[24:25], off nt
	v_lshlrev_b32_e32 v24, 2, v121
	v_or_b32_e32 v123, 52, v0
	global_load_dword v121, v24, s[12:13]
	v_mad_u64_u32 v[24:25], s[4:5], v123, s27, v[22:23]
	global_load_dword v124, v[24:25], off nt
	v_lshlrev_b32_e32 v24, 2, v123
	v_or_b32_e32 v125, 54, v0
	global_load_dword v123, v24, s[12:13]
	v_mad_u64_u32 v[24:25], s[4:5], v125, s27, v[22:23]
	global_load_dword v126, v[24:25], off nt
	v_lshlrev_b32_e32 v24, 2, v125
	v_or_b32_e32 v127, 56, v0
	global_load_dword v125, v24, s[12:13]
	v_mad_u64_u32 v[24:25], s[4:5], v127, s27, v[22:23]
	global_load_dword v128, v[24:25], off nt
	v_lshlrev_b32_e32 v24, 2, v127
	v_or_b32_e32 v129, 58, v0
	global_load_dword v127, v24, s[12:13]
	v_mad_u64_u32 v[24:25], s[4:5], v129, s27, v[22:23]
	global_load_dword v130, v[24:25], off nt
	v_lshlrev_b32_e32 v24, 2, v129
	v_or_b32_e32 v131, 60, v0
	v_or_b32_e32 v0, 62, v0
	global_load_dword v129, v24, s[12:13]
	v_mad_u64_u32 v[24:25], s[4:5], v131, s27, v[22:23]
	v_mad_u64_u32 v[22:23], s[4:5], v0, s27, v[22:23]
	global_load_dword v24, v[24:25], off nt
	v_lshlrev_b32_e32 v0, 2, v0
	global_load_dword v22, v[22:23], off nt
	v_lshlrev_b32_e32 v25, 2, v131
	global_load_dword v25, v25, s[12:13]
	s_waitcnt vmcnt(61)
	v_mul_f32_e32 v23, v26, v27
	global_load_dword v0, v0, s[12:13]
	s_waitcnt vmcnt(60)
	v_mul_f32_e32 v26, v74, v73
	ds_write2_b32 v29, v23, v26 offset1:66
	s_waitcnt vmcnt(58)
	v_mul_f32_e32 v23, v76, v75
	s_waitcnt vmcnt(56)
	v_mul_f32_e32 v26, v78, v77
	ds_write2_b32 v29, v23, v26 offset0:132 offset1:198
	s_waitcnt vmcnt(54)
	v_mul_f32_e32 v23, v80, v79
	s_waitcnt vmcnt(52)
	v_mul_f32_e32 v26, v82, v81
	ds_write2_b32 v35, v23, v26 offset0:8 offset1:74
	s_waitcnt vmcnt(50)
	v_mul_f32_e32 v23, v84, v83
	s_waitcnt vmcnt(48)
	v_mul_f32_e32 v26, v86, v85
	ds_write2_b32 v35, v23, v26 offset0:140 offset1:206
	s_waitcnt vmcnt(46)
	v_mul_f32_e32 v23, v88, v87
	s_waitcnt vmcnt(44)
	v_mul_f32_e32 v26, v90, v89
	ds_write2_b32 v36, v23, v26 offset0:16 offset1:82
	s_waitcnt vmcnt(42)
	v_mul_f32_e32 v23, v92, v91
	s_waitcnt vmcnt(40)
	v_mul_f32_e32 v26, v94, v93
	ds_write2_b32 v36, v23, v26 offset0:148 offset1:214
	s_waitcnt vmcnt(38)
	v_mul_f32_e32 v23, v96, v95
	s_waitcnt vmcnt(36)
	v_mul_f32_e32 v26, v98, v97
	ds_write2_b32 v37, v23, v26 offset0:24 offset1:90
	s_waitcnt vmcnt(34)
	v_mul_f32_e32 v23, v100, v99
	s_waitcnt vmcnt(32)
	v_mul_f32_e32 v26, v102, v101
	ds_write2_b32 v37, v23, v26 offset0:156 offset1:222
	s_waitcnt vmcnt(30)
	v_mul_f32_e32 v23, v104, v103
	s_waitcnt vmcnt(28)
	v_mul_f32_e32 v26, v106, v105
	ds_write2_b32 v38, v23, v26 offset0:32 offset1:98
	s_waitcnt vmcnt(26)
	v_mul_f32_e32 v23, v108, v107
	s_waitcnt vmcnt(24)
	v_mul_f32_e32 v26, v110, v109
	ds_write2_b32 v38, v23, v26 offset0:164 offset1:230
	s_waitcnt vmcnt(22)
	v_mul_f32_e32 v23, v112, v111
	s_waitcnt vmcnt(20)
	v_mul_f32_e32 v26, v114, v113
	ds_write2_b32 v39, v23, v26 offset0:40 offset1:106
	s_waitcnt vmcnt(18)
	v_mul_f32_e32 v23, v116, v115
	s_waitcnt vmcnt(16)
	v_mul_f32_e32 v26, v118, v117
	ds_write2_b32 v39, v23, v26 offset0:172 offset1:238
	s_lshl_b32 s4, s3, 5
	s_and_b32 s4, s4, 0x700
	s_waitcnt vmcnt(14)
	v_mul_f32_e32 v23, v120, v119
	s_and_b32 s0, s0, 0x80
	s_lshl_b32 s3, s3, 4
	s_or_b32 s0, s4, s0
	s_and_b32 s3, s3, 0x60
	s_or_b32 s3, s0, s3
	s_waitcnt vmcnt(12)
	v_mul_f32_e32 v26, v122, v121
	ds_write2_b32 v40, v23, v26 offset0:48 offset1:114
	s_lshl_b32 s0, s2, 7
	v_lshl_add_u64 v[88:89], v[2:3], 0, s[0:1]
	s_waitcnt vmcnt(10)
	v_mul_f32_e32 v23, v124, v123
	s_waitcnt vmcnt(8)
	v_mul_f32_e32 v26, v126, v125
	ds_write2_b32 v40, v23, v26 offset0:180 offset1:246
	s_waitcnt vmcnt(6)
	v_mul_f32_e32 v23, v128, v127
	s_waitcnt vmcnt(4)
	v_mul_f32_e32 v26, v130, v129
	ds_write2_b32 v41, v23, v26 offset0:56 offset1:122
	s_waitcnt vmcnt(1)
	v_mul_f32_e32 v23, v24, v25
	s_waitcnt vmcnt(0)
	v_mul_f32_e32 v0, v22, v0
	ds_write2_b32 v41, v23, v0 offset0:188 offset1:254
	s_waitcnt lgkmcnt(0)
	ds_read2_b32 v[26:27], v31 offset0:33 offset1:41
	ds_read2_b32 v[74:75], v31 offset1:8
	ds_read2_b32 v[76:77], v31 offset0:66 offset1:74
	ds_read2_b32 v[78:79], v31 offset0:99 offset1:107
	ds_read2_b32 v[80:81], v31 offset0:132 offset1:140
	ds_read2_b32 v[82:83], v31 offset0:165 offset1:173
	ds_read2_b32 v[84:85], v31 offset0:198 offset1:206
	ds_read2_b32 v[86:87], v31 offset0:231 offset1:239
	v_or_b32_e32 v0, s3, v30
	v_lshlrev_b32_e32 v0, 11, v0
	s_waitcnt lgkmcnt(6)
	v_cvt_pk_bf16_f32 v22, v74, v26
	s_waitcnt lgkmcnt(4)
	v_cvt_pk_bf16_f32 v23, v76, v78
	s_waitcnt lgkmcnt(2)
	v_cvt_pk_bf16_f32 v24, v80, v82
	s_waitcnt lgkmcnt(0)
	v_cvt_pk_bf16_f32 v25, v84, v86
	v_lshl_add_u64 v[90:91], v[88:89], 0, v[0:1]
	global_store_dwordx4 v[90:91], v[22:25], off
	v_or_b32_e32 v0, s3, v32
	v_lshlrev_b32_e32 v0, 11, v0
	v_cvt_pk_bf16_f32 v22, v75, v27
	v_cvt_pk_bf16_f32 v23, v77, v79
	v_cvt_pk_bf16_f32 v24, v81, v83
	v_cvt_pk_bf16_f32 v25, v85, v87
	ds_read2_b32 v[74:75], v31 offset0:49 offset1:57
	ds_read2_b32 v[76:77], v31 offset0:16 offset1:24
	ds_read2_b32 v[78:79], v31 offset0:82 offset1:90
	ds_read2_b32 v[80:81], v31 offset0:115 offset1:123
	ds_read2_b32 v[82:83], v31 offset0:148 offset1:156
	ds_read2_b32 v[84:85], v31 offset0:181 offset1:189
	ds_read2_b32 v[86:87], v31 offset0:214 offset1:222
	ds_read2_b32 v[90:91], v31 offset0:247 offset1:255
	v_lshl_add_u64 v[26:27], v[88:89], 0, v[0:1]
	v_or_b32_e32 v0, s3, v33
	v_lshlrev_b32_e32 v0, 11, v0
	global_store_dwordx4 v[26:27], v[22:25], off
	v_lshl_add_u64 v[26:27], v[88:89], 0, v[0:1]
	v_or_b32_e32 v0, s3, v34
	s_waitcnt lgkmcnt(6)
	v_cvt_pk_bf16_f32 v22, v76, v74
	s_waitcnt lgkmcnt(4)
	v_cvt_pk_bf16_f32 v23, v78, v80
	s_waitcnt lgkmcnt(2)
	v_cvt_pk_bf16_f32 v24, v82, v84
	s_waitcnt lgkmcnt(0)
	v_cvt_pk_bf16_f32 v25, v86, v90
	v_lshlrev_b32_e32 v0, 11, v0
	global_store_dwordx4 v[26:27], v[22:25], off
	v_lshl_add_u64 v[26:27], v[88:89], 0, v[0:1]
	s_mov_b64 s[2:3], 0
	v_cvt_pk_bf16_f32 v22, v77, v75
	v_cvt_pk_bf16_f32 v23, v79, v81
	v_cvt_pk_bf16_f32 v24, v83, v85
	v_cvt_pk_bf16_f32 v25, v87, v91
	global_store_dwordx4 v[26:27], v[22:25], off
	s_waitcnt lgkmcnt(0)
.LBB0_20:
	s_andn2_b64 vcc, exec, s[2:3]
	s_cbranch_vccnz .LBB0_22
	s_and_b32 s3, s25, 0x1ffc0
	s_and_b32 s2, s9, 0x3e0
	v_or_b32_e32 v0, s3, v28
	s_lshl_b32 s0, s2, 2
	v_lshl_add_u64 v[22:23], v[14:15], 0, s[0:1]
	v_lshlrev_b32_e32 v0, 12, v0
	v_lshl_add_u64 v[22:23], v[22:23], 0, v[0:1]
	v_add_co_u32_e32 v24, vcc, 0x2000, v22
	s_lshl_b32 s0, s3, 1
	s_nop 0
	v_addc_co_u32_e32 v25, vcc, 0, v23, vcc
	v_add_co_u32_e32 v26, vcc, 0x4000, v22
	s_nop 1
	v_addc_co_u32_e32 v27, vcc, 0, v23, vcc
	v_add_co_u32_e32 v74, vcc, 0x6000, v22
	s_nop 1
	v_addc_co_u32_e32 v75, vcc, 0, v23, vcc
	v_add_co_u32_e32 v76, vcc, 0x8000, v22
	s_nop 1
	v_addc_co_u32_e32 v77, vcc, 0, v23, vcc
	v_add_co_u32_e32 v78, vcc, 0xa000, v22
	s_nop 1
	v_addc_co_u32_e32 v79, vcc, 0, v23, vcc
	v_add_co_u32_e32 v80, vcc, 0xc000, v22
	s_nop 1
	v_addc_co_u32_e32 v81, vcc, 0, v23, vcc
	v_add_co_u32_e32 v82, vcc, 0xe000, v22
	s_nop 1
	v_addc_co_u32_e32 v83, vcc, 0, v23, vcc
	global_load_dword v0, v[22:23], off nt
	global_load_dword v73, v[24:25], off nt
	global_load_dword v86, v[26:27], off nt
	global_load_dword v87, v[74:75], off nt
	global_load_dword v88, v[76:77], off nt
	global_load_dword v89, v[78:79], off nt
	global_load_dword v90, v[80:81], off nt
	global_load_dword v91, v[82:83], off nt
	v_add_co_u32_e32 v24, vcc, 0x10000, v22
	s_nop 1
	v_addc_co_u32_e32 v25, vcc, 0, v23, vcc
	v_add_co_u32_e32 v26, vcc, 0x12000, v22
	s_nop 1
	v_addc_co_u32_e32 v27, vcc, 0, v23, vcc
	v_add_co_u32_e32 v74, vcc, 0x14000, v22
	s_nop 1
	v_addc_co_u32_e32 v75, vcc, 0, v23, vcc
	v_add_co_u32_e32 v76, vcc, 0x16000, v22
	s_nop 1
	v_addc_co_u32_e32 v77, vcc, 0, v23, vcc
	v_add_co_u32_e32 v78, vcc, 0x18000, v22
	s_nop 1
	v_addc_co_u32_e32 v79, vcc, 0, v23, vcc
	v_add_co_u32_e32 v80, vcc, 0x1a000, v22
	s_nop 1
	v_addc_co_u32_e32 v81, vcc, 0, v23, vcc
	v_add_co_u32_e32 v82, vcc, 0x1c000, v22
	s_nop 1
	v_addc_co_u32_e32 v83, vcc, 0, v23, vcc
	v_add_co_u32_e32 v84, vcc, s24, v22
	s_nop 1
	v_addc_co_u32_e32 v85, vcc, 0, v23, vcc
	global_load_dword v92, v[24:25], off nt
	global_load_dword v93, v[26:27], off nt
	global_load_dword v94, v[74:75], off nt
	global_load_dword v95, v[76:77], off nt
	global_load_dword v96, v[78:79], off nt
	global_load_dword v97, v[80:81], off nt
	global_load_dword v98, v[82:83], off nt
	global_load_dword v99, v[84:85], off nt
	v_add_co_u32_e32 v24, vcc, 0x20000, v22
	s_nop 1
	v_addc_co_u32_e32 v25, vcc, 0, v23, vcc
	v_add_co_u32_e32 v26, vcc, 0x22000, v22
	s_nop 1
	v_addc_co_u32_e32 v27, vcc, 0, v23, vcc
	v_add_co_u32_e32 v74, vcc, 0x24000, v22
	s_nop 1
	v_addc_co_u32_e32 v75, vcc, 0, v23, vcc
	v_add_co_u32_e32 v76, vcc, 0x26000, v22
	s_nop 1
	v_addc_co_u32_e32 v77, vcc, 0, v23, vcc
	v_add_co_u32_e32 v78, vcc, 0x28000, v22
	s_nop 1
	v_addc_co_u32_e32 v79, vcc, 0, v23, vcc
	v_add_co_u32_e32 v80, vcc, 0x2a000, v22
	s_nop 1
	v_addc_co_u32_e32 v81, vcc, 0, v23, vcc
	v_add_co_u32_e32 v82, vcc, 0x2c000, v22
	s_nop 1
	v_addc_co_u32_e32 v83, vcc, 0, v23, vcc
	v_add_co_u32_e32 v84, vcc, 0x2e000, v22
	s_nop 1
	v_addc_co_u32_e32 v85, vcc, 0, v23, vcc
	global_load_dword v100, v[24:25], off nt
	global_load_dword v101, v[26:27], off nt
	global_load_dword v102, v[74:75], off nt
	global_load_dword v103, v[76:77], off nt
	global_load_dword v104, v[78:79], off nt
	global_load_dword v105, v[80:81], off nt
	global_load_dword v106, v[82:83], off nt
	s_nop 0
	global_load_dword v84, v[84:85], off nt
	v_add_co_u32_e32 v24, vcc, 0x30000, v22
	s_nop 1
	v_addc_co_u32_e32 v25, vcc, 0, v23, vcc
	v_add_co_u32_e32 v26, vcc, 0x32000, v22
	s_nop 1
	v_addc_co_u32_e32 v27, vcc, 0, v23, vcc
	v_add_co_u32_e32 v74, vcc, 0x34000, v22
	s_nop 1
	v_addc_co_u32_e32 v75, vcc, 0, v23, vcc
	v_add_co_u32_e32 v76, vcc, 0x36000, v22
	s_nop 1
	v_addc_co_u32_e32 v77, vcc, 0, v23, vcc
	v_add_co_u32_e32 v78, vcc, 0x38000, v22
	s_nop 1
	v_addc_co_u32_e32 v79, vcc, 0, v23, vcc
	v_add_co_u32_e32 v80, vcc, 0x3a000, v22
	s_nop 1
	v_addc_co_u32_e32 v81, vcc, 0, v23, vcc
	v_add_co_u32_e32 v82, vcc, 0x3c000, v22
	s_nop 1
	v_addc_co_u32_e32 v83, vcc, 0, v23, vcc
	v_add_co_u32_e32 v22, vcc, 0x3e000, v22
	s_nop 1
	v_addc_co_u32_e32 v23, vcc, 0, v23, vcc
	global_load_dword v24, v[24:25], off nt
	s_nop 0
	global_load_dword v25, v[26:27], off nt
	s_nop 0
	global_load_dword v26, v[74:75], off nt
	global_load_dword v27, v[76:77], off nt
	s_nop 0
	global_load_dword v74, v[78:79], off nt
	global_load_dword v75, v[80:81], off nt
	global_load_dword v76, v[82:83], off nt
	s_nop 0
	global_load_dword v22, v[22:23], off nt
	s_waitcnt vmcnt(30)
	ds_write2_b32 v29, v0, v73 offset1:66
	s_waitcnt vmcnt(28)
	ds_write2_b32 v29, v86, v87 offset0:132 offset1:198
	s_waitcnt vmcnt(26)
	ds_write2_b32 v35, v88, v89 offset0:8 offset1:74
	s_waitcnt vmcnt(24)
	ds_write2_b32 v35, v90, v91 offset0:140 offset1:206
	s_waitcnt vmcnt(22)
	ds_write2_b32 v36, v92, v93 offset0:16 offset1:82
	s_waitcnt vmcnt(20)
	ds_write2_b32 v36, v94, v95 offset0:148 offset1:214
	s_waitcnt vmcnt(18)
	ds_write2_b32 v37, v96, v97 offset0:24 offset1:90
	s_waitcnt vmcnt(16)
	ds_write2_b32 v37, v98, v99 offset0:156 offset1:222
	s_waitcnt vmcnt(14)
	ds_write2_b32 v38, v100, v101 offset0:32 offset1:98
	s_waitcnt vmcnt(12)
	ds_write2_b32 v38, v102, v103 offset0:164 offset1:230
	s_waitcnt vmcnt(10)
	ds_write2_b32 v39, v104, v105 offset0:40 offset1:106
	s_waitcnt vmcnt(8)
	ds_write2_b32 v39, v106, v84 offset0:172 offset1:238
	s_waitcnt vmcnt(6)
	ds_write2_b32 v40, v24, v25 offset0:48 offset1:114
	s_waitcnt vmcnt(4)
	ds_write2_b32 v40, v26, v27 offset0:180 offset1:246
	s_waitcnt vmcnt(2)
	ds_write2_b32 v41, v74, v75 offset0:56 offset1:122
	s_waitcnt vmcnt(0)
	ds_write2_b32 v41, v76, v22 offset0:188 offset1:254
	s_waitcnt lgkmcnt(0)
	ds_read2_b32 v[26:27], v31 offset0:33 offset1:41
	ds_read2_b32 v[74:75], v31 offset1:8
	ds_read2_b32 v[76:77], v31 offset0:66 offset1:74
	ds_read2_b32 v[78:79], v31 offset0:99 offset1:107
	ds_read2_b32 v[80:81], v31 offset0:132 offset1:140
	ds_read2_b32 v[82:83], v31 offset0:165 offset1:173
	ds_read2_b32 v[84:85], v31 offset0:198 offset1:206
	ds_read2_b32 v[86:87], v31 offset0:231 offset1:239
	v_or_b32_e32 v0, s2, v30
	v_lshl_add_u64 v[88:89], v[4:5], 0, s[0:1]
	v_lshlrev_b32_e32 v0, 13, v0
	s_waitcnt lgkmcnt(6)
	v_cvt_pk_bf16_f32 v22, v74, v26
	s_waitcnt lgkmcnt(4)
	v_cvt_pk_bf16_f32 v23, v76, v78
	s_waitcnt lgkmcnt(2)
	v_cvt_pk_bf16_f32 v24, v80, v82
	s_waitcnt lgkmcnt(0)
	v_cvt_pk_bf16_f32 v25, v84, v86
	v_lshl_add_u64 v[90:91], v[88:89], 0, v[0:1]
	global_store_dwordx4 v[90:91], v[22:25], off
	v_or_b32_e32 v0, s2, v32
	v_lshlrev_b32_e32 v0, 13, v0
	v_cvt_pk_bf16_f32 v22, v75, v27
	v_cvt_pk_bf16_f32 v23, v77, v79
	v_cvt_pk_bf16_f32 v24, v81, v83
	v_cvt_pk_bf16_f32 v25, v85, v87
	ds_read2_b32 v[74:75], v31 offset0:49 offset1:57
	ds_read2_b32 v[76:77], v31 offset0:16 offset1:24
	ds_read2_b32 v[78:79], v31 offset0:82 offset1:90
	ds_read2_b32 v[80:81], v31 offset0:115 offset1:123
	ds_read2_b32 v[82:83], v31 offset0:148 offset1:156
	ds_read2_b32 v[84:85], v31 offset0:181 offset1:189
	ds_read2_b32 v[86:87], v31 offset0:214 offset1:222
	ds_read2_b32 v[90:91], v31 offset0:247 offset1:255
	v_lshl_add_u64 v[26:27], v[88:89], 0, v[0:1]
	v_or_b32_e32 v0, s2, v33
	v_lshlrev_b32_e32 v0, 13, v0
	global_store_dwordx4 v[26:27], v[22:25], off
	v_lshl_add_u64 v[26:27], v[88:89], 0, v[0:1]
	v_or_b32_e32 v0, s2, v34
	s_waitcnt lgkmcnt(6)
	v_cvt_pk_bf16_f32 v22, v76, v74
	s_waitcnt lgkmcnt(4)
	v_cvt_pk_bf16_f32 v23, v78, v80
	s_waitcnt lgkmcnt(2)
	v_cvt_pk_bf16_f32 v24, v82, v84
	s_waitcnt lgkmcnt(0)
	v_cvt_pk_bf16_f32 v25, v86, v90
	v_lshlrev_b32_e32 v0, 13, v0
	global_store_dwordx4 v[26:27], v[22:25], off
	v_lshl_add_u64 v[26:27], v[88:89], 0, v[0:1]
	s_nop 0
	v_cvt_pk_bf16_f32 v22, v77, v75
	v_cvt_pk_bf16_f32 v23, v79, v81
	v_cvt_pk_bf16_f32 v24, v83, v85
	v_cvt_pk_bf16_f32 v25, v87, v91
	global_store_dwordx4 v[26:27], v[22:25], off
	s_waitcnt lgkmcnt(0)

.LBB0_23:
	s_andn2_b64 vcc, exec, s[2:3]
	s_cbranch_vccnz .LBB0_89
	s_add_i32 s0, s29, 0xf800
	s_lshr_b32 s0, s0, 1
	s_and_b32 s3, s0, 0x7fc0
	s_and_b32 s2, s9, 0xfe0
	v_or_b32_e32 v27, s3, v28
	s_lshl_b32 s0, s2, 2
	v_lshl_add_u64 v[22:23], v[16:17], 0, s[0:1]
	v_lshlrev_b32_e32 v0, 14, v27
	v_lshl_add_u64 v[24:25], v[22:23], 0, v[0:1]
	global_load_dword v24, v[24:25], off nt
	v_cndmask_b32_e64 v0, 0, 1, s[14:15]
	v_mov_b32_e32 v26, 1.0
	v_cmp_ne_u32_e64 s[4:5], 1, v0
	s_andn2_b64 vcc, exec, s[14:15]
	v_lshlrev_b32_e32 v25, 2, v27
	v_mov_b32_e32 v73, 1.0
	s_cbranch_vccnz .LBB0_26
	v_readlane_b32 s36, v254, 13
	v_readlane_b32 s42, v254, 19
	v_readlane_b32 s43, v254, 20
	v_readlane_b32 s37, v254, 14
	v_readlane_b32 s38, v254, 15
	v_readlane_b32 s39, v254, 16
	v_readlane_b32 s40, v254, 17
	v_readlane_b32 s41, v254, 18
	global_load_dword v73, v25, s[42:43]
	v_readlane_b32 s44, v254, 21
	v_readlane_b32 s45, v254, 22
	v_readlane_b32 s46, v254, 23
	v_readlane_b32 s47, v254, 24
	v_readlane_b32 s48, v254, 25
	v_readlane_b32 s49, v254, 26
	v_readlane_b32 s50, v254, 27
	v_readlane_b32 s51, v254, 28
.LBB0_26:
	v_lshl_or_b32 v0, v27, 14, v42
	v_lshl_add_u64 v[74:75], v[22:23], 0, v[0:1]
	global_load_dword v74, v[74:75], off nt
	s_and_b64 vcc, exec, s[4:5]
	s_cbranch_vccnz .LBB0_28
	v_readlane_b32 s36, v254, 13
	v_readlane_b32 s42, v254, 19
	v_readlane_b32 s43, v254, 20
	v_readlane_b32 s37, v254, 14
	v_readlane_b32 s38, v254, 15
	v_readlane_b32 s39, v254, 16
	v_readlane_b32 s40, v254, 17
	v_readlane_b32 s41, v254, 18
	global_load_dword v26, v25, s[42:43] offset:8
	v_readlane_b32 s44, v254, 21
	v_readlane_b32 s45, v254, 22
	v_readlane_b32 s46, v254, 23
	v_readlane_b32 s47, v254, 24
	v_readlane_b32 s48, v254, 25
	v_readlane_b32 s49, v254, 26
	v_readlane_b32 s50, v254, 27
	v_readlane_b32 s51, v254, 28
.LBB0_28:
	v_lshl_or_b32 v0, v27, 14, v43
	v_lshl_add_u64 v[76:77], v[22:23], 0, v[0:1]
	global_load_dword v75, v[76:77], off nt
	v_mov_b32_e32 v76, 1.0
	s_and_b64 vcc, exec, s[4:5]
	v_mov_b32_e32 v77, 1.0
	s_cbranch_vccnz .LBB0_30
	v_readlane_b32 s36, v254, 13
	v_readlane_b32 s42, v254, 19
	v_readlane_b32 s43, v254, 20
	v_readlane_b32 s37, v254, 14
	v_readlane_b32 s38, v254, 15
	v_readlane_b32 s39, v254, 16
	v_readlane_b32 s40, v254, 17
	v_readlane_b32 s41, v254, 18
	global_load_dword v77, v25, s[42:43] offset:16
	v_readlane_b32 s44, v254, 21
	v_readlane_b32 s45, v254, 22
	v_readlane_b32 s46, v254, 23
	v_readlane_b32 s47, v254, 24
	v_readlane_b32 s48, v254, 25
	v_readlane_b32 s49, v254, 26
	v_readlane_b32 s50, v254, 27
	v_readlane_b32 s51, v254, 28
.LBB0_30:
	v_lshl_or_b32 v0, v27, 14, v44
	v_lshl_add_u64 v[78:79], v[22:23], 0, v[0:1]
	global_load_dword v78, v[78:79], off nt
	s_and_b64 vcc, exec, s[4:5]
	s_cbranch_vccnz .LBB0_32
	v_readlane_b32 s36, v254, 13
	v_readlane_b32 s42, v254, 19
	v_readlane_b32 s43, v254, 20
	v_readlane_b32 s37, v254, 14
	v_readlane_b32 s38, v254, 15
	v_readlane_b32 s39, v254, 16
	v_readlane_b32 s40, v254, 17
	v_readlane_b32 s41, v254, 18
	global_load_dword v76, v25, s[42:43] offset:24
	v_readlane_b32 s44, v254, 21
	v_readlane_b32 s45, v254, 22
	v_readlane_b32 s46, v254, 23
	v_readlane_b32 s47, v254, 24
	v_readlane_b32 s48, v254, 25
	v_readlane_b32 s49, v254, 26
	v_readlane_b32 s50, v254, 27
	v_readlane_b32 s51, v254, 28
.LBB0_32:
	v_lshl_or_b32 v0, v27, 14, v45
	v_lshl_add_u64 v[80:81], v[22:23], 0, v[0:1]
	global_load_dword v79, v[80:81], off nt
	v_mov_b32_e32 v80, 1.0
	s_and_b64 vcc, exec, s[4:5]
	v_mov_b32_e32 v81, 1.0
	s_cbranch_vccnz .LBB0_34
	v_readlane_b32 s36, v254, 13
	v_readlane_b32 s42, v254, 19
	v_readlane_b32 s43, v254, 20
	v_readlane_b32 s37, v254, 14
	v_readlane_b32 s38, v254, 15
	v_readlane_b32 s39, v254, 16
	v_readlane_b32 s40, v254, 17
	v_readlane_b32 s41, v254, 18
	global_load_dword v81, v25, s[42:43] offset:32
	v_readlane_b32 s44, v254, 21
	v_readlane_b32 s45, v254, 22
	v_readlane_b32 s46, v254, 23
	v_readlane_b32 s47, v254, 24
	v_readlane_b32 s48, v254, 25
	v_readlane_b32 s49, v254, 26
	v_readlane_b32 s50, v254, 27
	v_readlane_b32 s51, v254, 28
.LBB0_34:
	v_lshl_or_b32 v0, v27, 14, v46
	v_lshl_add_u64 v[82:83], v[22:23], 0, v[0:1]
	global_load_dword v82, v[82:83], off nt
	s_and_b64 vcc, exec, s[4:5]
	s_cbranch_vccnz .LBB0_36
	v_readlane_b32 s36, v254, 13
	v_readlane_b32 s42, v254, 19
	v_readlane_b32 s43, v254, 20
	v_readlane_b32 s37, v254, 14
	v_readlane_b32 s38, v254, 15
	v_readlane_b32 s39, v254, 16
	v_readlane_b32 s40, v254, 17
	v_readlane_b32 s41, v254, 18
	global_load_dword v80, v25, s[42:43] offset:40
	v_readlane_b32 s44, v254, 21
	v_readlane_b32 s45, v254, 22
	v_readlane_b32 s46, v254, 23
	v_readlane_b32 s47, v254, 24
	v_readlane_b32 s48, v254, 25
	v_readlane_b32 s49, v254, 26
	v_readlane_b32 s50, v254, 27
	v_readlane_b32 s51, v254, 28
.LBB0_36:
	v_lshl_or_b32 v0, v27, 14, v47
	v_lshl_add_u64 v[84:85], v[22:23], 0, v[0:1]
	global_load_dword v83, v[84:85], off nt
	v_mov_b32_e32 v84, 1.0
	s_and_b64 vcc, exec, s[4:5]
	v_mov_b32_e32 v85, 1.0
	s_cbranch_vccnz .LBB0_38
	v_readlane_b32 s36, v254, 13
	v_readlane_b32 s42, v254, 19
	v_readlane_b32 s43, v254, 20
	v_readlane_b32 s37, v254, 14
	v_readlane_b32 s38, v254, 15
	v_readlane_b32 s39, v254, 16
	v_readlane_b32 s40, v254, 17
	v_readlane_b32 s41, v254, 18
	global_load_dword v85, v25, s[42:43] offset:48
	v_readlane_b32 s44, v254, 21
	v_readlane_b32 s45, v254, 22
	v_readlane_b32 s46, v254, 23
	v_readlane_b32 s47, v254, 24
	v_readlane_b32 s48, v254, 25
	v_readlane_b32 s49, v254, 26
	v_readlane_b32 s50, v254, 27
	v_readlane_b32 s51, v254, 28
.LBB0_38:
	v_lshl_or_b32 v0, v27, 14, v48
	v_lshl_add_u64 v[86:87], v[22:23], 0, v[0:1]
	global_load_dword v86, v[86:87], off nt
	s_and_b64 vcc, exec, s[4:5]
	s_cbranch_vccnz .LBB0_40
	v_readlane_b32 s36, v254, 13
	v_readlane_b32 s42, v254, 19
	v_readlane_b32 s43, v254, 20
	v_readlane_b32 s37, v254, 14
	v_readlane_b32 s38, v254, 15
	v_readlane_b32 s39, v254, 16
	v_readlane_b32 s40, v254, 17
	v_readlane_b32 s41, v254, 18
	global_load_dword v84, v25, s[42:43] offset:56
	v_readlane_b32 s44, v254, 21
	v_readlane_b32 s45, v254, 22
	v_readlane_b32 s46, v254, 23
	v_readlane_b32 s47, v254, 24
	v_readlane_b32 s48, v254, 25
	v_readlane_b32 s49, v254, 26
	v_readlane_b32 s50, v254, 27
	v_readlane_b32 s51, v254, 28
.LBB0_40:
	v_lshl_or_b32 v0, v27, 14, v49
	v_lshl_add_u64 v[88:89], v[22:23], 0, v[0:1]
	global_load_dword v87, v[88:89], off nt
	v_mov_b32_e32 v88, 1.0
	s_and_b64 vcc, exec, s[4:5]
	v_mov_b32_e32 v89, 1.0
	s_cbranch_vccnz .LBB0_42
	v_readlane_b32 s36, v254, 13
	v_readlane_b32 s42, v254, 19
	v_readlane_b32 s43, v254, 20
	v_readlane_b32 s37, v254, 14
	v_readlane_b32 s38, v254, 15
	v_readlane_b32 s39, v254, 16
	v_readlane_b32 s40, v254, 17
	v_readlane_b32 s41, v254, 18
	global_load_dword v89, v25, s[42:43] offset:64
	v_readlane_b32 s44, v254, 21
	v_readlane_b32 s45, v254, 22
	v_readlane_b32 s46, v254, 23
	v_readlane_b32 s47, v254, 24
	v_readlane_b32 s48, v254, 25
	v_readlane_b32 s49, v254, 26
	v_readlane_b32 s50, v254, 27
	v_readlane_b32 s51, v254, 28
.LBB0_42:
	v_lshl_or_b32 v0, v27, 14, v50
	v_lshl_add_u64 v[90:91], v[22:23], 0, v[0:1]
	global_load_dword v90, v[90:91], off nt
	s_and_b64 vcc, exec, s[4:5]
	s_cbranch_vccnz .LBB0_44
	v_readlane_b32 s36, v254, 13
	v_readlane_b32 s42, v254, 19
	v_readlane_b32 s43, v254, 20
	v_readlane_b32 s37, v254, 14
	v_readlane_b32 s38, v254, 15
	v_readlane_b32 s39, v254, 16
	v_readlane_b32 s40, v254, 17
	v_readlane_b32 s41, v254, 18
	global_load_dword v88, v25, s[42:43] offset:72
	v_readlane_b32 s44, v254, 21
	v_readlane_b32 s45, v254, 22
	v_readlane_b32 s46, v254, 23
	v_readlane_b32 s47, v254, 24
	v_readlane_b32 s48, v254, 25
	v_readlane_b32 s49, v254, 26
	v_readlane_b32 s50, v254, 27
	v_readlane_b32 s51, v254, 28
.LBB0_44:
	v_lshl_or_b32 v0, v27, 14, v51
	v_lshl_add_u64 v[92:93], v[22:23], 0, v[0:1]
	global_load_dword v91, v[92:93], off nt
	v_mov_b32_e32 v92, 1.0
	s_and_b64 vcc, exec, s[4:5]
	v_mov_b32_e32 v93, 1.0
	s_cbranch_vccnz .LBB0_46
	v_readlane_b32 s36, v254, 13
	v_readlane_b32 s42, v254, 19
	v_readlane_b32 s43, v254, 20
	v_readlane_b32 s37, v254, 14
	v_readlane_b32 s38, v254, 15
	v_readlane_b32 s39, v254, 16
	v_readlane_b32 s40, v254, 17
	v_readlane_b32 s41, v254, 18
	global_load_dword v93, v25, s[42:43] offset:80
	v_readlane_b32 s44, v254, 21
	v_readlane_b32 s45, v254, 22
	v_readlane_b32 s46, v254, 23
	v_readlane_b32 s47, v254, 24
	v_readlane_b32 s48, v254, 25
	v_readlane_b32 s49, v254, 26
	v_readlane_b32 s50, v254, 27
	v_readlane_b32 s51, v254, 28
.LBB0_46:
	v_lshl_or_b32 v0, v27, 14, v52
	v_lshl_add_u64 v[94:95], v[22:23], 0, v[0:1]
	global_load_dword v94, v[94:95], off nt
	s_and_b64 vcc, exec, s[4:5]
	s_cbranch_vccnz .LBB0_48
	v_readlane_b32 s36, v254, 13
	v_readlane_b32 s42, v254, 19
	v_readlane_b32 s43, v254, 20
	v_readlane_b32 s37, v254, 14
	v_readlane_b32 s38, v254, 15
	v_readlane_b32 s39, v254, 16
	v_readlane_b32 s40, v254, 17
	v_readlane_b32 s41, v254, 18
	global_load_dword v92, v25, s[42:43] offset:88
	v_readlane_b32 s44, v254, 21
	v_readlane_b32 s45, v254, 22
	v_readlane_b32 s46, v254, 23
	v_readlane_b32 s47, v254, 24
	v_readlane_b32 s48, v254, 25
	v_readlane_b32 s49, v254, 26
	v_readlane_b32 s50, v254, 27
	v_readlane_b32 s51, v254, 28
.LBB0_48:
	v_lshl_or_b32 v0, v27, 14, v53
	v_lshl_add_u64 v[96:97], v[22:23], 0, v[0:1]
	global_load_dword v95, v[96:97], off nt
	v_mov_b32_e32 v96, 1.0
	s_and_b64 vcc, exec, s[4:5]
	v_mov_b32_e32 v97, 1.0
	s_cbranch_vccnz .LBB0_50
	v_readlane_b32 s36, v254, 13
	v_readlane_b32 s42, v254, 19
	v_readlane_b32 s43, v254, 20
	v_readlane_b32 s37, v254, 14
	v_readlane_b32 s38, v254, 15
	v_readlane_b32 s39, v254, 16
	v_readlane_b32 s40, v254, 17
	v_readlane_b32 s41, v254, 18
	global_load_dword v97, v25, s[42:43] offset:96
	v_readlane_b32 s44, v254, 21
	v_readlane_b32 s45, v254, 22
	v_readlane_b32 s46, v254, 23
	v_readlane_b32 s47, v254, 24
	v_readlane_b32 s48, v254, 25
	v_readlane_b32 s49, v254, 26
	v_readlane_b32 s50, v254, 27
	v_readlane_b32 s51, v254, 28
.LBB0_50:
	v_lshl_or_b32 v0, v27, 14, v54
	v_lshl_add_u64 v[98:99], v[22:23], 0, v[0:1]
	global_load_dword v98, v[98:99], off nt
	s_and_b64 vcc, exec, s[4:5]
	s_cbranch_vccnz .LBB0_52
	v_readlane_b32 s36, v254, 13
	v_readlane_b32 s42, v254, 19
	v_readlane_b32 s43, v254, 20
	v_readlane_b32 s37, v254, 14
	v_readlane_b32 s38, v254, 15
	v_readlane_b32 s39, v254, 16
	v_readlane_b32 s40, v254, 17
	v_readlane_b32 s41, v254, 18
	global_load_dword v96, v25, s[42:43] offset:104
	v_readlane_b32 s44, v254, 21
	v_readlane_b32 s45, v254, 22
	v_readlane_b32 s46, v254, 23
	v_readlane_b32 s47, v254, 24
	v_readlane_b32 s48, v254, 25
	v_readlane_b32 s49, v254, 26
	v_readlane_b32 s50, v254, 27
	v_readlane_b32 s51, v254, 28
.LBB0_52:
	v_lshl_or_b32 v0, v27, 14, v55
	v_lshl_add_u64 v[100:101], v[22:23], 0, v[0:1]
	global_load_dword v99, v[100:101], off nt
	v_mov_b32_e32 v100, 1.0
	s_and_b64 vcc, exec, s[4:5]
	v_mov_b32_e32 v101, 1.0
	s_cbranch_vccnz .LBB0_54
	v_readlane_b32 s36, v254, 13
	v_readlane_b32 s42, v254, 19
	v_readlane_b32 s43, v254, 20
	v_readlane_b32 s37, v254, 14
	v_readlane_b32 s38, v254, 15
	v_readlane_b32 s39, v254, 16
	v_readlane_b32 s40, v254, 17
	v_readlane_b32 s41, v254, 18
	global_load_dword v101, v25, s[42:43] offset:112
	v_readlane_b32 s44, v254, 21
	v_readlane_b32 s45, v254, 22
	v_readlane_b32 s46, v254, 23
	v_readlane_b32 s47, v254, 24
	v_readlane_b32 s48, v254, 25
	v_readlane_b32 s49, v254, 26
	v_readlane_b32 s50, v254, 27
	v_readlane_b32 s51, v254, 28
.LBB0_54:
	v_lshl_or_b32 v0, v27, 14, v56
	v_lshl_add_u64 v[102:103], v[22:23], 0, v[0:1]
	global_load_dword v102, v[102:103], off nt
	s_and_b64 vcc, exec, s[4:5]
	s_cbranch_vccnz .LBB0_56
	v_readlane_b32 s36, v254, 13
	v_readlane_b32 s42, v254, 19
	v_readlane_b32 s43, v254, 20
	v_readlane_b32 s37, v254, 14
	v_readlane_b32 s38, v254, 15
	v_readlane_b32 s39, v254, 16
	v_readlane_b32 s40, v254, 17
	v_readlane_b32 s41, v254, 18
	global_load_dword v100, v25, s[42:43] offset:120
	v_readlane_b32 s44, v254, 21
	v_readlane_b32 s45, v254, 22
	v_readlane_b32 s46, v254, 23
	v_readlane_b32 s47, v254, 24
	v_readlane_b32 s48, v254, 25
	v_readlane_b32 s49, v254, 26
	v_readlane_b32 s50, v254, 27
	v_readlane_b32 s51, v254, 28
.LBB0_56:
	v_lshl_or_b32 v0, v27, 14, v57
	v_lshl_add_u64 v[104:105], v[22:23], 0, v[0:1]
	global_load_dword v103, v[104:105], off nt
	v_mov_b32_e32 v104, 1.0
	s_and_b64 vcc, exec, s[4:5]
	v_mov_b32_e32 v105, 1.0
	s_cbranch_vccnz .LBB0_58
	v_readlane_b32 s36, v254, 13
	v_readlane_b32 s42, v254, 19
	v_readlane_b32 s43, v254, 20
	v_readlane_b32 s37, v254, 14
	v_readlane_b32 s38, v254, 15
	v_readlane_b32 s39, v254, 16
	v_readlane_b32 s40, v254, 17
	v_readlane_b32 s41, v254, 18
	global_load_dword v105, v25, s[42:43] offset:128
	v_readlane_b32 s44, v254, 21
	v_readlane_b32 s45, v254, 22
	v_readlane_b32 s46, v254, 23
	v_readlane_b32 s47, v254, 24
	v_readlane_b32 s48, v254, 25
	v_readlane_b32 s49, v254, 26
	v_readlane_b32 s50, v254, 27
	v_readlane_b32 s51, v254, 28
.LBB0_58:
	v_lshl_or_b32 v0, v27, 14, v58
	v_lshl_add_u64 v[106:107], v[22:23], 0, v[0:1]
	global_load_dword v106, v[106:107], off nt
	s_and_b64 vcc, exec, s[4:5]
	s_cbranch_vccnz .LBB0_60
	v_readlane_b32 s36, v254, 13
	v_readlane_b32 s42, v254, 19
	v_readlane_b32 s43, v254, 20
	v_readlane_b32 s37, v254, 14
	v_readlane_b32 s38, v254, 15
	v_readlane_b32 s39, v254, 16
	v_readlane_b32 s40, v254, 17
	v_readlane_b32 s41, v254, 18
	global_load_dword v104, v25, s[42:43] offset:136
	v_readlane_b32 s44, v254, 21
	v_readlane_b32 s45, v254, 22
	v_readlane_b32 s46, v254, 23
	v_readlane_b32 s47, v254, 24
	v_readlane_b32 s48, v254, 25
	v_readlane_b32 s49, v254, 26
	v_readlane_b32 s50, v254, 27
	v_readlane_b32 s51, v254, 28
.LBB0_60:
	v_lshl_or_b32 v0, v27, 14, v59
	v_lshl_add_u64 v[108:109], v[22:23], 0, v[0:1]
	global_load_dword v107, v[108:109], off nt
	v_mov_b32_e32 v108, 1.0
	s_and_b64 vcc, exec, s[4:5]
	v_mov_b32_e32 v109, 1.0
	s_cbranch_vccnz .LBB0_62
	v_readlane_b32 s36, v254, 13
	v_readlane_b32 s42, v254, 19
	v_readlane_b32 s43, v254, 20
	v_readlane_b32 s37, v254, 14
	v_readlane_b32 s38, v254, 15
	v_readlane_b32 s39, v254, 16
	v_readlane_b32 s40, v254, 17
	v_readlane_b32 s41, v254, 18
	global_load_dword v109, v25, s[42:43] offset:144
	v_readlane_b32 s44, v254, 21
	v_readlane_b32 s45, v254, 22
	v_readlane_b32 s46, v254, 23
	v_readlane_b32 s47, v254, 24
	v_readlane_b32 s48, v254, 25
	v_readlane_b32 s49, v254, 26
	v_readlane_b32 s50, v254, 27
	v_readlane_b32 s51, v254, 28
.LBB0_62:
	v_lshl_or_b32 v0, v27, 14, v60
	v_lshl_add_u64 v[110:111], v[22:23], 0, v[0:1]
	global_load_dword v110, v[110:111], off nt
	s_and_b64 vcc, exec, s[4:5]
	s_cbranch_vccnz .LBB0_64
	v_readlane_b32 s36, v254, 13
	v_readlane_b32 s42, v254, 19
	v_readlane_b32 s43, v254, 20
	v_readlane_b32 s37, v254, 14
	v_readlane_b32 s38, v254, 15
	v_readlane_b32 s39, v254, 16
	v_readlane_b32 s40, v254, 17
	v_readlane_b32 s41, v254, 18
	global_load_dword v108, v25, s[42:43] offset:152
	v_readlane_b32 s44, v254, 21
	v_readlane_b32 s45, v254, 22
	v_readlane_b32 s46, v254, 23
	v_readlane_b32 s47, v254, 24
	v_readlane_b32 s48, v254, 25
	v_readlane_b32 s49, v254, 26
	v_readlane_b32 s50, v254, 27
	v_readlane_b32 s51, v254, 28
.LBB0_64:
	v_lshl_or_b32 v0, v27, 14, v61
	v_lshl_add_u64 v[112:113], v[22:23], 0, v[0:1]
	global_load_dword v111, v[112:113], off nt
	v_mov_b32_e32 v112, 1.0
	s_and_b64 vcc, exec, s[4:5]
	v_mov_b32_e32 v113, 1.0
	s_cbranch_vccnz .LBB0_66
	v_readlane_b32 s36, v254, 13
	v_readlane_b32 s42, v254, 19
	v_readlane_b32 s43, v254, 20
	v_readlane_b32 s37, v254, 14
	v_readlane_b32 s38, v254, 15
	v_readlane_b32 s39, v254, 16
	v_readlane_b32 s40, v254, 17
	v_readlane_b32 s41, v254, 18
	global_load_dword v113, v25, s[42:43] offset:160
	v_readlane_b32 s44, v254, 21
	v_readlane_b32 s45, v254, 22
	v_readlane_b32 s46, v254, 23
	v_readlane_b32 s47, v254, 24
	v_readlane_b32 s48, v254, 25
	v_readlane_b32 s49, v254, 26
	v_readlane_b32 s50, v254, 27
	v_readlane_b32 s51, v254, 28
.LBB0_66:
	v_lshl_or_b32 v0, v27, 14, v62
	v_lshl_add_u64 v[114:115], v[22:23], 0, v[0:1]
	global_load_dword v114, v[114:115], off nt
	s_and_b64 vcc, exec, s[4:5]
	s_cbranch_vccnz .LBB0_68
	v_readlane_b32 s36, v254, 13
	v_readlane_b32 s42, v254, 19
	v_readlane_b32 s43, v254, 20
	v_readlane_b32 s37, v254, 14
	v_readlane_b32 s38, v254, 15
	v_readlane_b32 s39, v254, 16
	v_readlane_b32 s40, v254, 17
	v_readlane_b32 s41, v254, 18
	global_load_dword v112, v25, s[42:43] offset:168
	v_readlane_b32 s44, v254, 21
	v_readlane_b32 s45, v254, 22
	v_readlane_b32 s46, v254, 23
	v_readlane_b32 s47, v254, 24
	v_readlane_b32 s48, v254, 25
	v_readlane_b32 s49, v254, 26
	v_readlane_b32 s50, v254, 27
	v_readlane_b32 s51, v254, 28
.LBB0_68:
	v_lshl_or_b32 v0, v27, 14, v63
	v_lshl_add_u64 v[116:117], v[22:23], 0, v[0:1]
	global_load_dword v115, v[116:117], off nt
	v_mov_b32_e32 v116, 1.0
	s_and_b64 vcc, exec, s[4:5]
	v_mov_b32_e32 v117, 1.0
	s_cbranch_vccnz .LBB0_70
	v_readlane_b32 s36, v254, 13
	v_readlane_b32 s42, v254, 19
	v_readlane_b32 s43, v254, 20
	v_readlane_b32 s37, v254, 14
	v_readlane_b32 s38, v254, 15
	v_readlane_b32 s39, v254, 16
	v_readlane_b32 s40, v254, 17
	v_readlane_b32 s41, v254, 18
	global_load_dword v117, v25, s[42:43] offset:176
	v_readlane_b32 s44, v254, 21
	v_readlane_b32 s45, v254, 22
	v_readlane_b32 s46, v254, 23
	v_readlane_b32 s47, v254, 24
	v_readlane_b32 s48, v254, 25
	v_readlane_b32 s49, v254, 26
	v_readlane_b32 s50, v254, 27
	v_readlane_b32 s51, v254, 28
.LBB0_70:
	v_lshl_or_b32 v0, v27, 14, v64
	v_lshl_add_u64 v[118:119], v[22:23], 0, v[0:1]
	global_load_dword v118, v[118:119], off nt
	s_and_b64 vcc, exec, s[4:5]
	s_cbranch_vccnz .LBB0_72
	v_readlane_b32 s36, v254, 13
	v_readlane_b32 s42, v254, 19
	v_readlane_b32 s43, v254, 20
	v_readlane_b32 s37, v254, 14
	v_readlane_b32 s38, v254, 15
	v_readlane_b32 s39, v254, 16
	v_readlane_b32 s40, v254, 17
	v_readlane_b32 s41, v254, 18
	global_load_dword v116, v25, s[42:43] offset:184
	v_readlane_b32 s44, v254, 21
	v_readlane_b32 s45, v254, 22
	v_readlane_b32 s46, v254, 23
	v_readlane_b32 s47, v254, 24
	v_readlane_b32 s48, v254, 25
	v_readlane_b32 s49, v254, 26
	v_readlane_b32 s50, v254, 27
	v_readlane_b32 s51, v254, 28
.LBB0_72:
	v_lshl_or_b32 v0, v27, 14, v65
	v_lshl_add_u64 v[120:121], v[22:23], 0, v[0:1]
	global_load_dword v119, v[120:121], off nt
	v_mov_b32_e32 v120, 1.0
	s_and_b64 vcc, exec, s[4:5]
	v_mov_b32_e32 v121, 1.0
	s_cbranch_vccnz .LBB0_74
	v_readlane_b32 s36, v254, 13
	v_readlane_b32 s42, v254, 19
	v_readlane_b32 s43, v254, 20
	v_readlane_b32 s37, v254, 14
	v_readlane_b32 s38, v254, 15
	v_readlane_b32 s39, v254, 16
	v_readlane_b32 s40, v254, 17
	v_readlane_b32 s41, v254, 18
	global_load_dword v121, v25, s[42:43] offset:192
	v_readlane_b32 s44, v254, 21
	v_readlane_b32 s45, v254, 22
	v_readlane_b32 s46, v254, 23
	v_readlane_b32 s47, v254, 24
	v_readlane_b32 s48, v254, 25
	v_readlane_b32 s49, v254, 26
	v_readlane_b32 s50, v254, 27
	v_readlane_b32 s51, v254, 28
.LBB0_74:
	v_lshl_or_b32 v0, v27, 14, v66
	v_lshl_add_u64 v[122:123], v[22:23], 0, v[0:1]
	global_load_dword v122, v[122:123], off nt
	s_and_b64 vcc, exec, s[4:5]
	s_cbranch_vccnz .LBB0_76
	v_readlane_b32 s36, v254, 13
	v_readlane_b32 s42, v254, 19
	v_readlane_b32 s43, v254, 20
	v_readlane_b32 s37, v254, 14
	v_readlane_b32 s38, v254, 15
	v_readlane_b32 s39, v254, 16
	v_readlane_b32 s40, v254, 17
	v_readlane_b32 s41, v254, 18
	global_load_dword v120, v25, s[42:43] offset:200
	v_readlane_b32 s44, v254, 21
	v_readlane_b32 s45, v254, 22
	v_readlane_b32 s46, v254, 23
	v_readlane_b32 s47, v254, 24
	v_readlane_b32 s48, v254, 25
	v_readlane_b32 s49, v254, 26
	v_readlane_b32 s50, v254, 27
	v_readlane_b32 s51, v254, 28
.LBB0_76:
	v_lshl_or_b32 v0, v27, 14, v67
	v_lshl_add_u64 v[124:125], v[22:23], 0, v[0:1]
	global_load_dword v123, v[124:125], off nt
	v_mov_b32_e32 v124, 1.0
	s_and_b64 vcc, exec, s[4:5]
	v_mov_b32_e32 v125, 1.0
	s_cbranch_vccnz .LBB0_78
	v_readlane_b32 s36, v254, 13
	v_readlane_b32 s42, v254, 19
	v_readlane_b32 s43, v254, 20
	v_readlane_b32 s37, v254, 14
	v_readlane_b32 s38, v254, 15
	v_readlane_b32 s39, v254, 16
	v_readlane_b32 s40, v254, 17
	v_readlane_b32 s41, v254, 18
	global_load_dword v125, v25, s[42:43] offset:208
	v_readlane_b32 s44, v254, 21
	v_readlane_b32 s45, v254, 22
	v_readlane_b32 s46, v254, 23
	v_readlane_b32 s47, v254, 24
	v_readlane_b32 s48, v254, 25
	v_readlane_b32 s49, v254, 26
	v_readlane_b32 s50, v254, 27
	v_readlane_b32 s51, v254, 28
.LBB0_78:
	v_lshl_or_b32 v0, v27, 14, v68
	v_lshl_add_u64 v[126:127], v[22:23], 0, v[0:1]
	global_load_dword v126, v[126:127], off nt
	s_and_b64 vcc, exec, s[4:5]
	s_cbranch_vccnz .LBB0_80
	v_readlane_b32 s36, v254, 13
	v_readlane_b32 s42, v254, 19
	v_readlane_b32 s43, v254, 20
	v_readlane_b32 s37, v254, 14
	v_readlane_b32 s38, v254, 15
	v_readlane_b32 s39, v254, 16
	v_readlane_b32 s40, v254, 17
	v_readlane_b32 s41, v254, 18
	global_load_dword v124, v25, s[42:43] offset:216
	v_readlane_b32 s44, v254, 21
	v_readlane_b32 s45, v254, 22
	v_readlane_b32 s46, v254, 23
	v_readlane_b32 s47, v254, 24
	v_readlane_b32 s48, v254, 25
	v_readlane_b32 s49, v254, 26
	v_readlane_b32 s50, v254, 27
	v_readlane_b32 s51, v254, 28
.LBB0_80:
	v_lshl_or_b32 v0, v27, 14, v69
	v_lshl_add_u64 v[128:129], v[22:23], 0, v[0:1]
	global_load_dword v127, v[128:129], off nt
	v_mov_b32_e32 v128, 1.0
	s_and_b64 vcc, exec, s[4:5]
	v_mov_b32_e32 v129, 1.0
	s_cbranch_vccnz .LBB0_82
	v_readlane_b32 s36, v254, 13
	v_readlane_b32 s42, v254, 19
	v_readlane_b32 s43, v254, 20
	v_readlane_b32 s37, v254, 14
	v_readlane_b32 s38, v254, 15
	v_readlane_b32 s39, v254, 16
	v_readlane_b32 s40, v254, 17
	v_readlane_b32 s41, v254, 18
	global_load_dword v129, v25, s[42:43] offset:224
	v_readlane_b32 s44, v254, 21
	v_readlane_b32 s45, v254, 22
	v_readlane_b32 s46, v254, 23
	v_readlane_b32 s47, v254, 24
	v_readlane_b32 s48, v254, 25
	v_readlane_b32 s49, v254, 26
	v_readlane_b32 s50, v254, 27
	v_readlane_b32 s51, v254, 28
.LBB0_82:
	v_lshl_or_b32 v0, v27, 14, v70
	v_lshl_add_u64 v[130:131], v[22:23], 0, v[0:1]
	global_load_dword v130, v[130:131], off nt
	s_and_b64 vcc, exec, s[4:5]
	s_cbranch_vccnz .LBB0_84
	v_readlane_b32 s36, v254, 13
	v_readlane_b32 s42, v254, 19
	v_readlane_b32 s43, v254, 20
	v_readlane_b32 s37, v254, 14
	v_readlane_b32 s38, v254, 15
	v_readlane_b32 s39, v254, 16
	v_readlane_b32 s40, v254, 17
	v_readlane_b32 s41, v254, 18
	global_load_dword v128, v25, s[42:43] offset:232
	v_readlane_b32 s44, v254, 21
	v_readlane_b32 s45, v254, 22
	v_readlane_b32 s46, v254, 23
	v_readlane_b32 s47, v254, 24
	v_readlane_b32 s48, v254, 25
	v_readlane_b32 s49, v254, 26
	v_readlane_b32 s50, v254, 27
	v_readlane_b32 s51, v254, 28
.LBB0_84:
	v_lshl_or_b32 v0, v27, 14, v71
	v_lshl_add_u64 v[132:133], v[22:23], 0, v[0:1]
	global_load_dword v131, v[132:133], off nt
	v_mov_b32_e32 v132, 1.0
	s_and_b64 vcc, exec, s[4:5]
	v_mov_b32_e32 v133, 1.0
	s_cbranch_vccnz .LBB0_86
	v_readlane_b32 s36, v254, 13
	v_readlane_b32 s42, v254, 19
	v_readlane_b32 s43, v254, 20
	v_readlane_b32 s37, v254, 14
	v_readlane_b32 s38, v254, 15
	v_readlane_b32 s39, v254, 16
	v_readlane_b32 s40, v254, 17
	v_readlane_b32 s41, v254, 18
	global_load_dword v133, v25, s[42:43] offset:240
	v_readlane_b32 s44, v254, 21
	v_readlane_b32 s45, v254, 22
	v_readlane_b32 s46, v254, 23
	v_readlane_b32 s47, v254, 24
	v_readlane_b32 s48, v254, 25
	v_readlane_b32 s49, v254, 26
	v_readlane_b32 s50, v254, 27
	v_readlane_b32 s51, v254, 28
.LBB0_86:
	v_lshl_or_b32 v0, v27, 14, v72
	v_lshl_add_u64 v[22:23], v[22:23], 0, v[0:1]
	global_load_dword v0, v[22:23], off nt
	s_and_b64 vcc, exec, s[4:5]
	s_cbranch_vccnz .LBB0_88
	v_readlane_b32 s36, v254, 13
	v_readlane_b32 s42, v254, 19
	v_readlane_b32 s43, v254, 20
	v_readlane_b32 s37, v254, 14
	v_readlane_b32 s38, v254, 15
	v_readlane_b32 s39, v254, 16
	v_readlane_b32 s40, v254, 17
	v_readlane_b32 s41, v254, 18
	global_load_dword v132, v25, s[42:43] offset:248
	v_readlane_b32 s44, v254, 21
	v_readlane_b32 s45, v254, 22
	v_readlane_b32 s46, v254, 23
	v_readlane_b32 s47, v254, 24
	v_readlane_b32 s48, v254, 25
	v_readlane_b32 s49, v254, 26
	v_readlane_b32 s50, v254, 27
	v_readlane_b32 s51, v254, 28

.LBB0_90:
	s_andn2_b64 vcc, exec, s[2:3]
	s_cbranch_vccnz .LBB0_92
	s_add_i32 s0, s25, 0x1400
	s_and_b32 s3, s0, 0x1ffc0
	s_and_b32 s2, s9, 0x3e0
	v_or_b32_e32 v0, s3, v28
	s_lshl_b32 s0, s2, 2
	v_lshl_add_u64 v[22:23], v[18:19], 0, s[0:1]
	v_lshlrev_b32_e32 v0, 12, v0
	v_lshl_add_u64 v[22:23], v[22:23], 0, v[0:1]
	v_add_co_u32_e32 v24, vcc, 0x2000, v22
	s_lshl_b32 s0, s3, 1
	s_nop 0
	v_addc_co_u32_e32 v25, vcc, 0, v23, vcc
	v_add_co_u32_e32 v26, vcc, 0x4000, v22
	s_nop 1
	v_addc_co_u32_e32 v27, vcc, 0, v23, vcc
	v_add_co_u32_e32 v74, vcc, 0x6000, v22
	s_nop 1
	v_addc_co_u32_e32 v75, vcc, 0, v23, vcc
	v_add_co_u32_e32 v76, vcc, 0x8000, v22
	s_nop 1
	v_addc_co_u32_e32 v77, vcc, 0, v23, vcc
	v_add_co_u32_e32 v78, vcc, 0xa000, v22
	s_nop 1
	v_addc_co_u32_e32 v79, vcc, 0, v23, vcc
	v_add_co_u32_e32 v80, vcc, 0xc000, v22
	s_nop 1
	v_addc_co_u32_e32 v81, vcc, 0, v23, vcc
	v_add_co_u32_e32 v82, vcc, 0xe000, v22
	s_nop 1
	v_addc_co_u32_e32 v83, vcc, 0, v23, vcc
	global_load_dword v0, v[22:23], off nt
	global_load_dword v73, v[24:25], off nt
	global_load_dword v86, v[26:27], off nt
	global_load_dword v87, v[74:75], off nt
	global_load_dword v88, v[76:77], off nt
	global_load_dword v89, v[78:79], off nt
	global_load_dword v90, v[80:81], off nt
	global_load_dword v91, v[82:83], off nt
	v_add_co_u32_e32 v24, vcc, 0x10000, v22
	s_nop 1
	v_addc_co_u32_e32 v25, vcc, 0, v23, vcc
	v_add_co_u32_e32 v26, vcc, 0x12000, v22
	s_nop 1
	v_addc_co_u32_e32 v27, vcc, 0, v23, vcc
	v_add_co_u32_e32 v74, vcc, 0x14000, v22
	s_nop 1
	v_addc_co_u32_e32 v75, vcc, 0, v23, vcc
	v_add_co_u32_e32 v76, vcc, 0x16000, v22
	s_nop 1
	v_addc_co_u32_e32 v77, vcc, 0, v23, vcc
	v_add_co_u32_e32 v78, vcc, 0x18000, v22
	s_nop 1
	v_addc_co_u32_e32 v79, vcc, 0, v23, vcc
	v_add_co_u32_e32 v80, vcc, 0x1a000, v22
	s_nop 1
	v_addc_co_u32_e32 v81, vcc, 0, v23, vcc
	v_add_co_u32_e32 v82, vcc, 0x1c000, v22
	s_nop 1
	v_addc_co_u32_e32 v83, vcc, 0, v23, vcc
	v_add_co_u32_e32 v84, vcc, s24, v22
	s_nop 1
	v_addc_co_u32_e32 v85, vcc, 0, v23, vcc
	global_load_dword v92, v[24:25], off nt
	global_load_dword v93, v[26:27], off nt
	global_load_dword v94, v[74:75], off nt
	global_load_dword v95, v[76:77], off nt
	global_load_dword v96, v[78:79], off nt
	global_load_dword v97, v[80:81], off nt
	global_load_dword v98, v[82:83], off nt
	global_load_dword v99, v[84:85], off nt
	v_add_co_u32_e32 v24, vcc, 0x20000, v22
	s_nop 1
	v_addc_co_u32_e32 v25, vcc, 0, v23, vcc
	v_add_co_u32_e32 v26, vcc, 0x22000, v22
	s_nop 1
	v_addc_co_u32_e32 v27, vcc, 0, v23, vcc
	v_add_co_u32_e32 v74, vcc, 0x24000, v22
	s_nop 1
	v_addc_co_u32_e32 v75, vcc, 0, v23, vcc
	v_add_co_u32_e32 v76, vcc, 0x26000, v22
	s_nop 1
	v_addc_co_u32_e32 v77, vcc, 0, v23, vcc
	v_add_co_u32_e32 v78, vcc, 0x28000, v22
	s_nop 1
	v_addc_co_u32_e32 v79, vcc, 0, v23, vcc
	v_add_co_u32_e32 v80, vcc, 0x2a000, v22
	s_nop 1
	v_addc_co_u32_e32 v81, vcc, 0, v23, vcc
	v_add_co_u32_e32 v82, vcc, 0x2c000, v22
	s_nop 1
	v_addc_co_u32_e32 v83, vcc, 0, v23, vcc
	v_add_co_u32_e32 v84, vcc, 0x2e000, v22
	s_nop 1
	v_addc_co_u32_e32 v85, vcc, 0, v23, vcc
	global_load_dword v100, v[24:25], off nt
	global_load_dword v101, v[26:27], off nt
	global_load_dword v102, v[74:75], off nt
	global_load_dword v103, v[76:77], off nt
	global_load_dword v104, v[78:79], off nt
	global_load_dword v105, v[80:81], off nt
	global_load_dword v106, v[82:83], off nt
	s_nop 0
	global_load_dword v84, v[84:85], off nt
	v_add_co_u32_e32 v24, vcc, 0x30000, v22
	s_nop 1
	v_addc_co_u32_e32 v25, vcc, 0, v23, vcc
	v_add_co_u32_e32 v26, vcc, 0x32000, v22
	s_nop 1
	v_addc_co_u32_e32 v27, vcc, 0, v23, vcc
	v_add_co_u32_e32 v74, vcc, 0x34000, v22
	s_nop 1
	v_addc_co_u32_e32 v75, vcc, 0, v23, vcc
	v_add_co_u32_e32 v76, vcc, 0x36000, v22
	s_nop 1
	v_addc_co_u32_e32 v77, vcc, 0, v23, vcc
	v_add_co_u32_e32 v78, vcc, 0x38000, v22
	s_nop 1
	v_addc_co_u32_e32 v79, vcc, 0, v23, vcc
	v_add_co_u32_e32 v80, vcc, 0x3a000, v22
	s_nop 1
	v_addc_co_u32_e32 v81, vcc, 0, v23, vcc
	v_add_co_u32_e32 v82, vcc, 0x3c000, v22
	s_nop 1
	v_addc_co_u32_e32 v83, vcc, 0, v23, vcc
	v_add_co_u32_e32 v22, vcc, 0x3e000, v22
	s_nop 1
	v_addc_co_u32_e32 v23, vcc, 0, v23, vcc
	global_load_dword v24, v[24:25], off nt
	s_nop 0
	global_load_dword v25, v[26:27], off nt
	s_nop 0
	global_load_dword v26, v[74:75], off nt
	global_load_dword v27, v[76:77], off nt
	s_nop 0
	global_load_dword v74, v[78:79], off nt
	global_load_dword v75, v[80:81], off nt
	global_load_dword v76, v[82:83], off nt
	s_nop 0
	global_load_dword v22, v[22:23], off nt
	s_waitcnt vmcnt(30)
	ds_write2_b32 v29, v0, v73 offset1:66
	s_waitcnt vmcnt(28)
	ds_write2_b32 v29, v86, v87 offset0:132 offset1:198
	s_waitcnt vmcnt(26)
	ds_write2_b32 v35, v88, v89 offset0:8 offset1:74
	s_waitcnt vmcnt(24)
	ds_write2_b32 v35, v90, v91 offset0:140 offset1:206
	s_waitcnt vmcnt(22)
	ds_write2_b32 v36, v92, v93 offset0:16 offset1:82
	s_waitcnt vmcnt(20)
	ds_write2_b32 v36, v94, v95 offset0:148 offset1:214
	s_waitcnt vmcnt(18)
	ds_write2_b32 v37, v96, v97 offset0:24 offset1:90
	s_waitcnt vmcnt(16)
	ds_write2_b32 v37, v98, v99 offset0:156 offset1:222
	s_waitcnt vmcnt(14)
	ds_write2_b32 v38, v100, v101 offset0:32 offset1:98
	s_waitcnt vmcnt(12)
	ds_write2_b32 v38, v102, v103 offset0:164 offset1:230
	s_waitcnt vmcnt(10)
	ds_write2_b32 v39, v104, v105 offset0:40 offset1:106
	s_waitcnt vmcnt(8)
	ds_write2_b32 v39, v106, v84 offset0:172 offset1:238
	s_waitcnt vmcnt(6)
	ds_write2_b32 v40, v24, v25 offset0:48 offset1:114
	s_waitcnt vmcnt(4)
	ds_write2_b32 v40, v26, v27 offset0:180 offset1:246
	s_waitcnt vmcnt(2)
	ds_write2_b32 v41, v74, v75 offset0:56 offset1:122
	s_waitcnt vmcnt(0)
	ds_write2_b32 v41, v76, v22 offset0:188 offset1:254
	s_waitcnt lgkmcnt(0)
	ds_read2_b32 v[26:27], v31 offset0:33 offset1:41
	ds_read2_b32 v[74:75], v31 offset1:8
	ds_read2_b32 v[76:77], v31 offset0:66 offset1:74
	ds_read2_b32 v[78:79], v31 offset0:99 offset1:107
	ds_read2_b32 v[80:81], v31 offset0:132 offset1:140
	ds_read2_b32 v[82:83], v31 offset0:165 offset1:173
	ds_read2_b32 v[84:85], v31 offset0:198 offset1:206
	ds_read2_b32 v[86:87], v31 offset0:231 offset1:239
	v_or_b32_e32 v0, s2, v30
	v_lshl_add_u64 v[88:89], v[8:9], 0, s[0:1]
	v_lshlrev_b32_e32 v0, 11, v0
	s_waitcnt lgkmcnt(6)
	v_cvt_pk_bf16_f32 v22, v74, v26
	s_waitcnt lgkmcnt(4)
	v_cvt_pk_bf16_f32 v23, v76, v78
	s_waitcnt lgkmcnt(2)
	v_cvt_pk_bf16_f32 v24, v80, v82
	s_waitcnt lgkmcnt(0)
	v_cvt_pk_bf16_f32 v25, v84, v86
	v_lshl_add_u64 v[90:91], v[88:89], 0, v[0:1]
	global_store_dwordx4 v[90:91], v[22:25], off
	v_or_b32_e32 v0, s2, v32
	v_lshlrev_b32_e32 v0, 11, v0
	v_cvt_pk_bf16_f32 v22, v75, v27
	v_cvt_pk_bf16_f32 v23, v77, v79
	v_cvt_pk_bf16_f32 v24, v81, v83
	v_cvt_pk_bf16_f32 v25, v85, v87
	ds_read2_b32 v[74:75], v31 offset0:49 offset1:57
	ds_read2_b32 v[76:77], v31 offset0:16 offset1:24
	ds_read2_b32 v[78:79], v31 offset0:82 offset1:90
	ds_read2_b32 v[80:81], v31 offset0:115 offset1:123
	ds_read2_b32 v[82:83], v31 offset0:148 offset1:156
	ds_read2_b32 v[84:85], v31 offset0:181 offset1:189
	ds_read2_b32 v[86:87], v31 offset0:214 offset1:222
	ds_read2_b32 v[90:91], v31 offset0:247 offset1:255
	v_lshl_add_u64 v[26:27], v[88:89], 0, v[0:1]
	v_or_b32_e32 v0, s2, v33
	v_lshlrev_b32_e32 v0, 11, v0
	global_store_dwordx4 v[26:27], v[22:25], off
	v_lshl_add_u64 v[26:27], v[88:89], 0, v[0:1]
	v_or_b32_e32 v0, s2, v34
	s_waitcnt lgkmcnt(6)
	v_cvt_pk_bf16_f32 v22, v76, v74
	s_waitcnt lgkmcnt(4)
	v_cvt_pk_bf16_f32 v23, v78, v80
	s_waitcnt lgkmcnt(2)
	v_cvt_pk_bf16_f32 v24, v82, v84
	s_waitcnt lgkmcnt(0)
	v_cvt_pk_bf16_f32 v25, v86, v90
	v_lshlrev_b32_e32 v0, 11, v0
	global_store_dwordx4 v[26:27], v[22:25], off
	v_lshl_add_u64 v[26:27], v[88:89], 0, v[0:1]
	s_nop 0
	v_cvt_pk_bf16_f32 v22, v77, v75
	v_cvt_pk_bf16_f32 v23, v79, v81
	v_cvt_pk_bf16_f32 v24, v83, v85
	v_cvt_pk_bf16_f32 v25, v87, v91
	global_store_dwordx4 v[26:27], v[22:25], off
	s_waitcnt lgkmcnt(0)

.LBB0_93:
	s_andn2_b64 vcc, exec, s[2:3]
	s_cbranch_vccnz .LBB0_14
	s_mul_hi_i32 s0, s29, 0x2aaaaaab
	s_lshr_b32 s2, s0, 31
	s_ashr_i32 s0, s0, 4
	s_add_i32 s0, s0, s2
	s_lshl_b32 s2, s0, 6
	s_mulk_i32 s0, 0xf400
	s_add_i32 s18, s9, s0
	s_ashr_i32 s19, s18, 31
	v_or_b32_e32 v22, s2, v28
	v_lshl_add_u64 v[24:25], s[18:19], 2, v[20:21]
	v_mad_i64_i32 v[26:27], s[4:5], v22, s28, v[24:25]
	global_load_dword v0, v[26:27], off nt
	v_readlane_b32 s36, v254, 13
	v_ashrrev_i32_e32 v23, 31, v22
	v_cndmask_b32_e64 v26, 0, 1, s[16:17]
	v_readlane_b32 s40, v254, 17
	v_readlane_b32 s41, v254, 18
	v_mov_b32_e32 v73, 1.0
	v_cmp_ne_u32_e64 s[4:5], 1, v26
	s_andn2_b64 vcc, exec, s[16:17]
	v_lshl_add_u64 v[26:27], v[22:23], 2, s[40:41]
	v_mov_b32_e32 v23, 1.0
	v_readlane_b32 s37, v254, 14
	v_readlane_b32 s38, v254, 15
	v_readlane_b32 s39, v254, 16
	v_readlane_b32 s42, v254, 19
	v_readlane_b32 s43, v254, 20
	v_readlane_b32 s44, v254, 21
	v_readlane_b32 s45, v254, 22
	v_readlane_b32 s46, v254, 23
	v_readlane_b32 s47, v254, 24
	v_readlane_b32 s48, v254, 25
	v_readlane_b32 s49, v254, 26
	v_readlane_b32 s50, v254, 27
	v_readlane_b32 s51, v254, 28
	s_cbranch_vccnz .LBB0_96
	global_load_dword v23, v[26:27], off nt
.LBB0_96:
	v_or_b32_e32 v74, 2, v22
	v_mad_i64_i32 v[74:75], s[30:31], v74, s28, v[24:25]
	global_load_dword v74, v[74:75], off nt
	s_and_b64 vcc, exec, s[4:5]
	s_cbranch_vccnz .LBB0_98
	global_load_dword v73, v[26:27], off offset:8 nt
.LBB0_98:
	v_or_b32_e32 v75, 4, v22
	v_mad_i64_i32 v[76:77], s[30:31], v75, s28, v[24:25]
	global_load_dword v75, v[76:77], off nt
	v_mov_b32_e32 v76, 1.0
	s_and_b64 vcc, exec, s[4:5]
	v_mov_b32_e32 v77, 1.0
	s_cbranch_vccnz .LBB0_100
	global_load_dword v77, v[26:27], off offset:16 nt
.LBB0_100:
	v_or_b32_e32 v78, 6, v22
	v_mad_i64_i32 v[78:79], s[30:31], v78, s28, v[24:25]
	global_load_dword v78, v[78:79], off nt
	s_and_b64 vcc, exec, s[4:5]
	s_cbranch_vccnz .LBB0_102
	global_load_dword v76, v[26:27], off offset:24 nt
.LBB0_102:
	v_or_b32_e32 v79, 8, v22
	v_mad_i64_i32 v[80:81], s[30:31], v79, s28, v[24:25]
	global_load_dword v79, v[80:81], off nt
	v_mov_b32_e32 v80, 1.0
	s_and_b64 vcc, exec, s[4:5]
	v_mov_b32_e32 v81, 1.0
	s_cbranch_vccnz .LBB0_104
	global_load_dword v81, v[26:27], off offset:32 nt
.LBB0_104:
	v_or_b32_e32 v82, 10, v22
	v_mad_i64_i32 v[82:83], s[30:31], v82, s28, v[24:25]
	global_load_dword v82, v[82:83], off nt
	s_and_b64 vcc, exec, s[4:5]
	s_cbranch_vccnz .LBB0_106
	global_load_dword v80, v[26:27], off offset:40 nt
.LBB0_106:
	v_or_b32_e32 v83, 12, v22
	v_mad_i64_i32 v[84:85], s[30:31], v83, s28, v[24:25]
	global_load_dword v83, v[84:85], off nt
	v_mov_b32_e32 v84, 1.0
	s_and_b64 vcc, exec, s[4:5]
	v_mov_b32_e32 v85, 1.0
	s_cbranch_vccnz .LBB0_108
	global_load_dword v85, v[26:27], off offset:48 nt
.LBB0_108:
	v_or_b32_e32 v86, 14, v22
	v_mad_i64_i32 v[86:87], s[30:31], v86, s28, v[24:25]
	global_load_dword v86, v[86:87], off nt
	s_and_b64 vcc, exec, s[4:5]
	s_cbranch_vccnz .LBB0_110
	global_load_dword v84, v[26:27], off offset:56 nt
.LBB0_110:
	v_or_b32_e32 v87, 16, v22
	v_mad_i64_i32 v[88:89], s[30:31], v87, s28, v[24:25]
	global_load_dword v87, v[88:89], off nt
	v_mov_b32_e32 v88, 1.0
	s_and_b64 vcc, exec, s[4:5]
	v_mov_b32_e32 v89, 1.0
	s_cbranch_vccnz .LBB0_112
	global_load_dword v89, v[26:27], off offset:64 nt
.LBB0_112:
	v_or_b32_e32 v90, 18, v22
	v_mad_i64_i32 v[90:91], s[30:31], v90, s28, v[24:25]
	global_load_dword v90, v[90:91], off nt
	s_and_b64 vcc, exec, s[4:5]
	s_cbranch_vccnz .LBB0_114
	global_load_dword v88, v[26:27], off offset:72 nt
.LBB0_114:
	v_or_b32_e32 v91, 20, v22
	v_mad_i64_i32 v[92:93], s[30:31], v91, s28, v[24:25]
	global_load_dword v91, v[92:93], off nt
	v_mov_b32_e32 v92, 1.0
	s_and_b64 vcc, exec, s[4:5]
	v_mov_b32_e32 v93, 1.0
	s_cbranch_vccnz .LBB0_116
	global_load_dword v93, v[26:27], off offset:80 nt
.LBB0_116:
	v_or_b32_e32 v94, 22, v22
	v_mad_i64_i32 v[94:95], s[30:31], v94, s28, v[24:25]
	global_load_dword v94, v[94:95], off nt
	s_and_b64 vcc, exec, s[4:5]
	s_cbranch_vccnz .LBB0_118
	global_load_dword v92, v[26:27], off offset:88 nt
.LBB0_118:
	v_or_b32_e32 v95, 24, v22
	v_mad_i64_i32 v[96:97], s[30:31], v95, s28, v[24:25]
	global_load_dword v95, v[96:97], off nt
	v_mov_b32_e32 v96, 1.0
	s_and_b64 vcc, exec, s[4:5]
	v_mov_b32_e32 v97, 1.0
	s_cbranch_vccnz .LBB0_120
	global_load_dword v97, v[26:27], off offset:96 nt
.LBB0_120:
	v_or_b32_e32 v98, 26, v22
	v_mad_i64_i32 v[98:99], s[30:31], v98, s28, v[24:25]
	global_load_dword v98, v[98:99], off nt
	s_and_b64 vcc, exec, s[4:5]
	s_cbranch_vccnz .LBB0_122
	global_load_dword v96, v[26:27], off offset:104 nt
.LBB0_122:
	v_or_b32_e32 v99, 28, v22
	v_mad_i64_i32 v[100:101], s[30:31], v99, s28, v[24:25]
	global_load_dword v99, v[100:101], off nt
	v_mov_b32_e32 v100, 1.0
	s_and_b64 vcc, exec, s[4:5]
	v_mov_b32_e32 v101, 1.0
	s_cbranch_vccnz .LBB0_124
	global_load_dword v101, v[26:27], off offset:112 nt
.LBB0_124:
	v_or_b32_e32 v102, 30, v22
	v_mad_i64_i32 v[102:103], s[30:31], v102, s28, v[24:25]
	global_load_dword v102, v[102:103], off nt
	s_and_b64 vcc, exec, s[4:5]
	s_cbranch_vccnz .LBB0_126
	global_load_dword v100, v[26:27], off offset:120 nt
.LBB0_126:
	v_or_b32_e32 v103, 32, v22
	v_mad_i64_i32 v[104:105], s[30:31], v103, s28, v[24:25]
	global_load_dword v103, v[104:105], off nt
	v_mov_b32_e32 v104, 1.0
	s_and_b64 vcc, exec, s[4:5]
	v_mov_b32_e32 v105, 1.0
	s_cbranch_vccnz .LBB0_128
	global_load_dword v105, v[26:27], off offset:128 nt
.LBB0_128:
	v_or_b32_e32 v106, 34, v22
	v_mad_i64_i32 v[106:107], s[30:31], v106, s28, v[24:25]
	global_load_dword v106, v[106:107], off nt
	s_and_b64 vcc, exec, s[4:5]
	s_cbranch_vccnz .LBB0_130
	global_load_dword v104, v[26:27], off offset:136 nt
.LBB0_130:
	v_or_b32_e32 v107, 36, v22
	v_mad_i64_i32 v[108:109], s[30:31], v107, s28, v[24:25]
	global_load_dword v107, v[108:109], off nt
	v_mov_b32_e32 v108, 1.0
	s_and_b64 vcc, exec, s[4:5]
	v_mov_b32_e32 v109, 1.0
	s_cbranch_vccnz .LBB0_132
	global_load_dword v109, v[26:27], off offset:144 nt
.LBB0_132:
	v_or_b32_e32 v110, 38, v22
	v_mad_i64_i32 v[110:111], s[30:31], v110, s28, v[24:25]
	global_load_dword v110, v[110:111], off nt
	s_and_b64 vcc, exec, s[4:5]
	s_cbranch_vccnz .LBB0_134
	global_load_dword v108, v[26:27], off offset:152 nt
.LBB0_134:
	v_or_b32_e32 v111, 40, v22
	v_mad_i64_i32 v[112:113], s[30:31], v111, s28, v[24:25]
	global_load_dword v111, v[112:113], off nt
	v_mov_b32_e32 v112, 1.0
	s_and_b64 vcc, exec, s[4:5]
	v_mov_b32_e32 v113, 1.0
	s_cbranch_vccnz .LBB0_136
	global_load_dword v113, v[26:27], off offset:160 nt
.LBB0_136:
	v_or_b32_e32 v114, 42, v22
	v_mad_i64_i32 v[114:115], s[30:31], v114, s28, v[24:25]
	global_load_dword v114, v[114:115], off nt
	s_and_b64 vcc, exec, s[4:5]
	s_cbranch_vccnz .LBB0_138
	global_load_dword v112, v[26:27], off offset:168 nt
.LBB0_138:
	v_or_b32_e32 v115, 44, v22
	v_mad_i64_i32 v[116:117], s[30:31], v115, s28, v[24:25]
	global_load_dword v115, v[116:117], off nt
	v_mov_b32_e32 v116, 1.0
	s_and_b64 vcc, exec, s[4:5]
	v_mov_b32_e32 v117, 1.0
	s_cbranch_vccnz .LBB0_140
	global_load_dword v117, v[26:27], off offset:176 nt
.LBB0_140:
	v_or_b32_e32 v118, 46, v22
	v_mad_i64_i32 v[118:119], s[30:31], v118, s28, v[24:25]
	global_load_dword v118, v[118:119], off nt
	s_and_b64 vcc, exec, s[4:5]
	s_cbranch_vccnz .LBB0_142
	global_load_dword v116, v[26:27], off offset:184 nt
.LBB0_142:
	v_or_b32_e32 v119, 48, v22
	v_mad_i64_i32 v[120:121], s[30:31], v119, s28, v[24:25]
	global_load_dword v119, v[120:121], off nt
	v_mov_b32_e32 v120, 1.0
	s_and_b64 vcc, exec, s[4:5]
	v_mov_b32_e32 v121, 1.0
	s_cbranch_vccnz .LBB0_144
	global_load_dword v121, v[26:27], off offset:192 nt
.LBB0_144:
	v_or_b32_e32 v122, 50, v22
	v_mad_i64_i32 v[122:123], s[30:31], v122, s28, v[24:25]
	global_load_dword v122, v[122:123], off nt
	s_and_b64 vcc, exec, s[4:5]
	s_cbranch_vccnz .LBB0_146
	global_load_dword v120, v[26:27], off offset:200 nt
.LBB0_146:
	v_or_b32_e32 v123, 52, v22
	v_mad_i64_i32 v[124:125], s[30:31], v123, s28, v[24:25]
	global_load_dword v123, v[124:125], off nt
	v_mov_b32_e32 v124, 1.0
	s_and_b64 vcc, exec, s[4:5]
	v_mov_b32_e32 v125, 1.0
	s_cbranch_vccnz .LBB0_148
	global_load_dword v125, v[26:27], off offset:208 nt
.LBB0_148:
	v_or_b32_e32 v126, 54, v22
	v_mad_i64_i32 v[126:127], s[30:31], v126, s28, v[24:25]
	global_load_dword v126, v[126:127], off nt
	s_and_b64 vcc, exec, s[4:5]
	s_cbranch_vccnz .LBB0_150
	global_load_dword v124, v[26:27], off offset:216 nt
.LBB0_150:
	v_or_b32_e32 v127, 56, v22
	v_mad_i64_i32 v[128:129], s[30:31], v127, s28, v[24:25]
	global_load_dword v127, v[128:129], off nt
	v_mov_b32_e32 v128, 1.0
	s_and_b64 vcc, exec, s[4:5]
	v_mov_b32_e32 v129, 1.0
	s_cbranch_vccnz .LBB0_152
	global_load_dword v129, v[26:27], off offset:224 nt
.LBB0_152:
	v_or_b32_e32 v130, 58, v22
	v_mad_i64_i32 v[130:131], s[30:31], v130, s28, v[24:25]
	global_load_dword v130, v[130:131], off nt
	s_and_b64 vcc, exec, s[4:5]
	s_cbranch_vccnz .LBB0_154
	global_load_dword v128, v[26:27], off offset:232 nt
.LBB0_154:
	v_or_b32_e32 v131, 60, v22
	v_mad_i64_i32 v[132:133], s[30:31], v131, s28, v[24:25]
	global_load_dword v131, v[132:133], off nt
	v_mov_b32_e32 v132, 1.0
	s_and_b64 vcc, exec, s[4:5]
	v_mov_b32_e32 v133, 1.0
	s_cbranch_vccnz .LBB0_156
	global_load_dword v133, v[26:27], off offset:240 nt
.LBB0_156:
	v_or_b32_e32 v22, 62, v22
	v_mad_i64_i32 v[24:25], s[30:31], v22, s28, v[24:25]
	global_load_dword v22, v[24:25], off nt
	s_and_b64 vcc, exec, s[4:5]
	s_cbranch_vccnz .LBB0_13
	global_load_dword v132, v[26:27], off offset:248 nt
	s_branch .LBB0_13

.LBB0_836:
	s_cmpk_gt_i32 s8, 0x7ff
	s_mov_b64 s[4:5], -1
	s_cbranch_scc0 .LBB0_842
	s_and_b32 s6, s10, 0x3e0
	s_cmpk_gt_u32 s8, 0x9ff
	v_or_b32_e32 v17, s6, v19
	v_or_b32_e32 v16, s6, v21
	v_or_b32_e32 v15, s6, v22
	v_or_b32_e32 v14, s6, v23
	s_cbranch_scc0 .LBB0_839
	s_and_b32 s4, s12, 0x1ffc0
	v_or_b32_e32 v0, s4, v229
	s_lshl_b32 s0, s6, 2
	v_lshl_add_u64 v[32:33], v[4:5], 0, s[0:1]
	v_lshlrev_b32_e32 v0, 12, v0
	v_lshl_add_u64 v[32:33], v[32:33], 0, v[0:1]
	v_add_co_u32_e32 v34, vcc, 0x2000, v32
	s_lshl_b32 s0, s4, 1
	s_nop 0
	v_addc_co_u32_e32 v35, vcc, 0, v33, vcc
	v_add_co_u32_e32 v36, vcc, 0x4000, v32
	s_mov_b64 s[4:5], 0
	s_nop 0
	v_addc_co_u32_e32 v37, vcc, 0, v33, vcc
	v_add_co_u32_e32 v38, vcc, 0x6000, v32
	s_nop 1
	v_addc_co_u32_e32 v39, vcc, 0, v33, vcc
	v_add_co_u32_e32 v40, vcc, 0x8000, v32
	s_nop 1
	v_addc_co_u32_e32 v41, vcc, 0, v33, vcc
	v_add_co_u32_e32 v42, vcc, 0xa000, v32
	s_nop 1
	v_addc_co_u32_e32 v43, vcc, 0, v33, vcc
	v_add_co_u32_e32 v44, vcc, 0xc000, v32
	s_nop 1
	v_addc_co_u32_e32 v45, vcc, 0, v33, vcc
	v_add_co_u32_e32 v46, vcc, 0xe000, v32
	s_nop 1
	v_addc_co_u32_e32 v47, vcc, 0, v33, vcc
	global_load_dword v0, v[32:33], off nt
	global_load_dword v31, v[34:35], off nt
	global_load_dword v50, v[36:37], off nt
	global_load_dword v51, v[38:39], off nt
	global_load_dword v52, v[40:41], off nt
	global_load_dword v53, v[42:43], off nt
	global_load_dword v54, v[44:45], off nt
	global_load_dword v55, v[46:47], off nt
	v_add_co_u32_e32 v34, vcc, 0x10000, v32
	s_nop 1
	v_addc_co_u32_e32 v35, vcc, 0, v33, vcc
	v_add_co_u32_e32 v36, vcc, 0x12000, v32
	s_nop 1
	v_addc_co_u32_e32 v37, vcc, 0, v33, vcc
	v_add_co_u32_e32 v38, vcc, 0x14000, v32
	s_nop 1
	v_addc_co_u32_e32 v39, vcc, 0, v33, vcc
	v_add_co_u32_e32 v40, vcc, 0x16000, v32
	s_nop 1
	v_addc_co_u32_e32 v41, vcc, 0, v33, vcc
	v_add_co_u32_e32 v42, vcc, 0x18000, v32
	s_nop 1
	v_addc_co_u32_e32 v43, vcc, 0, v33, vcc
	v_add_co_u32_e32 v44, vcc, 0x1a000, v32
	s_nop 1
	v_addc_co_u32_e32 v45, vcc, 0, v33, vcc
	v_add_co_u32_e32 v46, vcc, 0x1c000, v32
	s_nop 1
	v_addc_co_u32_e32 v47, vcc, 0, v33, vcc
	v_add_co_u32_e32 v48, vcc, 0x1e000, v32
	s_nop 1
	v_addc_co_u32_e32 v49, vcc, 0, v33, vcc
	global_load_dword v56, v[34:35], off nt
	global_load_dword v57, v[36:37], off nt
	global_load_dword v58, v[38:39], off nt
	global_load_dword v59, v[40:41], off nt
	global_load_dword v60, v[42:43], off nt
	global_load_dword v61, v[44:45], off nt
	global_load_dword v62, v[46:47], off nt
	global_load_dword v63, v[48:49], off nt
	v_add_co_u32_e32 v34, vcc, 0x20000, v32
	s_nop 1
	v_addc_co_u32_e32 v35, vcc, 0, v33, vcc
	v_add_co_u32_e32 v36, vcc, 0x22000, v32
	s_nop 1
	v_addc_co_u32_e32 v37, vcc, 0, v33, vcc
	v_add_co_u32_e32 v38, vcc, 0x24000, v32
	s_nop 1
	v_addc_co_u32_e32 v39, vcc, 0, v33, vcc
	v_add_co_u32_e32 v40, vcc, 0x26000, v32
	s_nop 1
	v_addc_co_u32_e32 v41, vcc, 0, v33, vcc
	v_add_co_u32_e32 v42, vcc, 0x28000, v32
	s_nop 1
	v_addc_co_u32_e32 v43, vcc, 0, v33, vcc
	v_add_co_u32_e32 v44, vcc, 0x2a000, v32
	s_nop 1
	v_addc_co_u32_e32 v45, vcc, 0, v33, vcc
	v_add_co_u32_e32 v46, vcc, 0x2c000, v32
	s_nop 1
	v_addc_co_u32_e32 v47, vcc, 0, v33, vcc
	v_add_co_u32_e32 v48, vcc, 0x2e000, v32
	s_nop 1
	v_addc_co_u32_e32 v49, vcc, 0, v33, vcc
	global_load_dword v64, v[34:35], off nt
	global_load_dword v65, v[36:37], off nt
	global_load_dword v66, v[38:39], off nt
	global_load_dword v67, v[40:41], off nt
	global_load_dword v68, v[42:43], off nt
	global_load_dword v69, v[44:45], off nt
	global_load_dword v70, v[46:47], off nt
	s_nop 0
	global_load_dword v48, v[48:49], off nt
	v_add_co_u32_e32 v34, vcc, 0x30000, v32
	s_nop 1
	v_addc_co_u32_e32 v35, vcc, 0, v33, vcc
	v_add_co_u32_e32 v36, vcc, 0x32000, v32
	s_nop 1
	v_addc_co_u32_e32 v37, vcc, 0, v33, vcc
	v_add_co_u32_e32 v38, vcc, 0x34000, v32
	s_nop 1
	v_addc_co_u32_e32 v39, vcc, 0, v33, vcc
	v_add_co_u32_e32 v40, vcc, 0x36000, v32
	s_nop 1
	v_addc_co_u32_e32 v41, vcc, 0, v33, vcc
	v_add_co_u32_e32 v42, vcc, 0x38000, v32
	s_nop 1
	v_addc_co_u32_e32 v43, vcc, 0, v33, vcc
	v_add_co_u32_e32 v44, vcc, 0x3a000, v32
	s_nop 1
	v_addc_co_u32_e32 v45, vcc, 0, v33, vcc
	v_add_co_u32_e32 v46, vcc, 0x3c000, v32
	s_nop 1
	v_addc_co_u32_e32 v47, vcc, 0, v33, vcc
	v_add_co_u32_e32 v32, vcc, 0x3e000, v32
	s_nop 1
	v_addc_co_u32_e32 v33, vcc, 0, v33, vcc
	global_load_dword v34, v[34:35], off nt
	s_nop 0
	global_load_dword v35, v[36:37], off nt
	s_nop 0
	global_load_dword v36, v[38:39], off nt
	global_load_dword v37, v[40:41], off nt
	s_nop 0
	global_load_dword v38, v[42:43], off nt
	global_load_dword v39, v[44:45], off nt
	global_load_dword v40, v[46:47], off nt
	s_nop 0
	global_load_dword v32, v[32:33], off nt
	s_waitcnt vmcnt(30)
	ds_write2_b32 v18, v0, v31 offset1:66
	s_waitcnt vmcnt(28)
	ds_write2_b32 v18, v50, v51 offset0:132 offset1:198
	s_waitcnt vmcnt(26)
	ds_write2_b32 v24, v52, v53 offset0:8 offset1:74
	s_waitcnt vmcnt(24)
	ds_write2_b32 v24, v54, v55 offset0:140 offset1:206
	s_waitcnt vmcnt(22)
	ds_write2_b32 v25, v56, v57 offset0:16 offset1:82
	s_waitcnt vmcnt(20)
	ds_write2_b32 v25, v58, v59 offset0:148 offset1:214
	s_waitcnt vmcnt(18)
	ds_write2_b32 v26, v60, v61 offset0:24 offset1:90
	s_waitcnt vmcnt(16)
	ds_write2_b32 v26, v62, v63 offset0:156 offset1:222
	s_waitcnt vmcnt(14)
	ds_write2_b32 v27, v64, v65 offset0:32 offset1:98
	s_waitcnt vmcnt(12)
	ds_write2_b32 v27, v66, v67 offset0:164 offset1:230
	s_waitcnt vmcnt(10)
	ds_write2_b32 v28, v68, v69 offset0:40 offset1:106
	s_waitcnt vmcnt(8)
	ds_write2_b32 v28, v70, v48 offset0:172 offset1:238
	s_waitcnt vmcnt(6)
	ds_write2_b32 v29, v34, v35 offset0:48 offset1:114
	s_waitcnt vmcnt(4)
	ds_write2_b32 v29, v36, v37 offset0:180 offset1:246
	s_waitcnt vmcnt(2)
	ds_write2_b32 v30, v38, v39 offset0:56 offset1:122
	s_waitcnt vmcnt(0)
	ds_write2_b32 v30, v40, v32 offset0:188 offset1:254
	s_waitcnt lgkmcnt(0)
	ds_read2_b32 v[36:37], v20 offset0:33 offset1:41
	ds_read2_b32 v[38:39], v20 offset1:8
	ds_read2_b32 v[40:41], v20 offset0:66 offset1:74
	ds_read2_b32 v[42:43], v20 offset0:99 offset1:107
	ds_read2_b32 v[44:45], v20 offset0:132 offset1:140
	ds_read2_b32 v[46:47], v20 offset0:165 offset1:173
	ds_read2_b32 v[48:49], v20 offset0:198 offset1:206
	ds_read2_b32 v[50:51], v20 offset0:231 offset1:239
	v_lshl_add_u64 v[52:53], v[6:7], 0, s[0:1]
	v_lshlrev_b32_e32 v0, 13, v17
	s_waitcnt lgkmcnt(6)
	v_cvt_pk_bf16_f32 v32, v38, v36
	s_waitcnt lgkmcnt(4)
	v_cvt_pk_bf16_f32 v33, v40, v42
	s_waitcnt lgkmcnt(2)
	v_cvt_pk_bf16_f32 v34, v44, v46
	s_waitcnt lgkmcnt(0)
	v_cvt_pk_bf16_f32 v35, v48, v50
	v_lshl_add_u64 v[54:55], v[52:53], 0, v[0:1]
	global_store_dwordx4 v[54:55], v[32:35], off
	v_lshlrev_b32_e32 v0, 13, v16
	s_nop 0
	v_cvt_pk_bf16_f32 v32, v39, v37
	v_cvt_pk_bf16_f32 v33, v41, v43
	v_cvt_pk_bf16_f32 v34, v45, v47
	v_cvt_pk_bf16_f32 v35, v49, v51
	ds_read2_b32 v[38:39], v20 offset0:49 offset1:57
	ds_read2_b32 v[40:41], v20 offset0:16 offset1:24
	ds_read2_b32 v[42:43], v20 offset0:82 offset1:90
	ds_read2_b32 v[44:45], v20 offset0:115 offset1:123
	ds_read2_b32 v[46:47], v20 offset0:148 offset1:156
	ds_read2_b32 v[48:49], v20 offset0:181 offset1:189
	ds_read2_b32 v[50:51], v20 offset0:214 offset1:222
	ds_read2_b32 v[54:55], v20 offset0:247 offset1:255
	v_lshl_add_u64 v[36:37], v[52:53], 0, v[0:1]
	v_lshlrev_b32_e32 v0, 13, v15
	global_store_dwordx4 v[36:37], v[32:35], off
	v_lshl_add_u64 v[36:37], v[52:53], 0, v[0:1]
	v_lshlrev_b32_e32 v0, 13, v14
	s_waitcnt lgkmcnt(6)
	v_cvt_pk_bf16_f32 v32, v40, v38
	s_waitcnt lgkmcnt(4)
	v_cvt_pk_bf16_f32 v33, v42, v44
	s_waitcnt lgkmcnt(2)
	v_cvt_pk_bf16_f32 v34, v46, v48
	s_waitcnt lgkmcnt(0)
	v_cvt_pk_bf16_f32 v35, v50, v54
	global_store_dwordx4 v[36:37], v[32:35], off
	v_lshl_add_u64 v[36:37], v[52:53], 0, v[0:1]
	s_nop 0
	v_cvt_pk_bf16_f32 v32, v41, v39
	v_cvt_pk_bf16_f32 v33, v43, v45
	v_cvt_pk_bf16_f32 v34, v47, v49
	v_cvt_pk_bf16_f32 v35, v51, v55
	global_store_dwordx4 v[36:37], v[32:35], off
	s_waitcnt lgkmcnt(0)
.LBB0_839:
	s_andn2_b64 vcc, exec, s[4:5]
	s_cbranch_vccnz .LBB0_841
	s_add_i32 s0, s12, 0x400
	s_and_b32 s4, s0, 0x1ffc0
	v_or_b32_e32 v0, s4, v229
	s_lshl_b32 s0, s6, 2
	v_lshl_add_u64 v[32:33], v[2:3], 0, s[0:1]
	v_lshlrev_b32_e32 v0, 12, v0
	v_lshl_add_u64 v[32:33], v[32:33], 0, v[0:1]
	v_add_co_u32_e32 v34, vcc, 0x2000, v32
	s_lshl_b32 s0, s4, 1
	s_nop 0
	v_addc_co_u32_e32 v35, vcc, 0, v33, vcc
	v_add_co_u32_e32 v36, vcc, 0x4000, v32
	s_nop 1
	v_addc_co_u32_e32 v37, vcc, 0, v33, vcc
	v_add_co_u32_e32 v38, vcc, 0x6000, v32
	s_nop 1
	v_addc_co_u32_e32 v39, vcc, 0, v33, vcc
	v_add_co_u32_e32 v40, vcc, 0x8000, v32
	s_nop 1
	v_addc_co_u32_e32 v41, vcc, 0, v33, vcc
	v_add_co_u32_e32 v42, vcc, 0xa000, v32
	s_nop 1
	v_addc_co_u32_e32 v43, vcc, 0, v33, vcc
	v_add_co_u32_e32 v44, vcc, 0xc000, v32
	s_nop 1
	v_addc_co_u32_e32 v45, vcc, 0, v33, vcc
	v_add_co_u32_e32 v46, vcc, 0xe000, v32
	s_nop 1
	v_addc_co_u32_e32 v47, vcc, 0, v33, vcc
	global_load_dword v0, v[32:33], off nt
	global_load_dword v31, v[34:35], off nt
	global_load_dword v50, v[36:37], off nt
	global_load_dword v51, v[38:39], off nt
	global_load_dword v52, v[40:41], off nt
	global_load_dword v53, v[42:43], off nt
	global_load_dword v54, v[44:45], off nt
	global_load_dword v55, v[46:47], off nt
	v_add_co_u32_e32 v34, vcc, 0x10000, v32
	s_nop 1
	v_addc_co_u32_e32 v35, vcc, 0, v33, vcc
	v_add_co_u32_e32 v36, vcc, 0x12000, v32
	s_nop 1
	v_addc_co_u32_e32 v37, vcc, 0, v33, vcc
	v_add_co_u32_e32 v38, vcc, 0x14000, v32
	s_nop 1
	v_addc_co_u32_e32 v39, vcc, 0, v33, vcc
	v_add_co_u32_e32 v40, vcc, 0x16000, v32
	s_nop 1
	v_addc_co_u32_e32 v41, vcc, 0, v33, vcc
	v_add_co_u32_e32 v42, vcc, 0x18000, v32
	s_nop 1
	v_addc_co_u32_e32 v43, vcc, 0, v33, vcc
	v_add_co_u32_e32 v44, vcc, 0x1a000, v32
	s_nop 1
	v_addc_co_u32_e32 v45, vcc, 0, v33, vcc
	v_add_co_u32_e32 v46, vcc, 0x1c000, v32
	s_nop 1
	v_addc_co_u32_e32 v47, vcc, 0, v33, vcc
	v_add_co_u32_e32 v48, vcc, 0x1e000, v32
	s_nop 1
	v_addc_co_u32_e32 v49, vcc, 0, v33, vcc
	global_load_dword v56, v[34:35], off nt
	global_load_dword v57, v[36:37], off nt
	global_load_dword v58, v[38:39], off nt
	global_load_dword v59, v[40:41], off nt
	global_load_dword v60, v[42:43], off nt
	global_load_dword v61, v[44:45], off nt
	global_load_dword v62, v[46:47], off nt
	global_load_dword v63, v[48:49], off nt
	v_add_co_u32_e32 v34, vcc, 0x20000, v32
	s_nop 1
	v_addc_co_u32_e32 v35, vcc, 0, v33, vcc
	v_add_co_u32_e32 v36, vcc, 0x22000, v32
	s_nop 1
	v_addc_co_u32_e32 v37, vcc, 0, v33, vcc
	v_add_co_u32_e32 v38, vcc, 0x24000, v32
	s_nop 1
	v_addc_co_u32_e32 v39, vcc, 0, v33, vcc
	v_add_co_u32_e32 v40, vcc, 0x26000, v32
	s_nop 1
	v_addc_co_u32_e32 v41, vcc, 0, v33, vcc
	v_add_co_u32_e32 v42, vcc, 0x28000, v32
	s_nop 1
	v_addc_co_u32_e32 v43, vcc, 0, v33, vcc
	v_add_co_u32_e32 v44, vcc, 0x2a000, v32
	s_nop 1
	v_addc_co_u32_e32 v45, vcc, 0, v33, vcc
	v_add_co_u32_e32 v46, vcc, 0x2c000, v32
	s_nop 1
	v_addc_co_u32_e32 v47, vcc, 0, v33, vcc
	v_add_co_u32_e32 v48, vcc, 0x2e000, v32
	s_nop 1
	v_addc_co_u32_e32 v49, vcc, 0, v33, vcc
	global_load_dword v64, v[34:35], off nt
	global_load_dword v65, v[36:37], off nt
	global_load_dword v66, v[38:39], off nt
	global_load_dword v67, v[40:41], off nt
	global_load_dword v68, v[42:43], off nt
	global_load_dword v69, v[44:45], off nt
	global_load_dword v70, v[46:47], off nt
	s_nop 0
	global_load_dword v48, v[48:49], off nt
	v_add_co_u32_e32 v34, vcc, 0x30000, v32
	s_nop 1
	v_addc_co_u32_e32 v35, vcc, 0, v33, vcc
	v_add_co_u32_e32 v36, vcc, 0x32000, v32
	s_nop 1
	v_addc_co_u32_e32 v37, vcc, 0, v33, vcc
	v_add_co_u32_e32 v38, vcc, 0x34000, v32
	s_nop 1
	v_addc_co_u32_e32 v39, vcc, 0, v33, vcc
	v_add_co_u32_e32 v40, vcc, 0x36000, v32
	s_nop 1
	v_addc_co_u32_e32 v41, vcc, 0, v33, vcc
	v_add_co_u32_e32 v42, vcc, 0x38000, v32
	s_nop 1
	v_addc_co_u32_e32 v43, vcc, 0, v33, vcc
	v_add_co_u32_e32 v44, vcc, 0x3a000, v32
	s_nop 1
	v_addc_co_u32_e32 v45, vcc, 0, v33, vcc
	v_add_co_u32_e32 v46, vcc, 0x3c000, v32
	s_nop 1
	v_addc_co_u32_e32 v47, vcc, 0, v33, vcc
	v_add_co_u32_e32 v32, vcc, 0x3e000, v32
	s_nop 1
	v_addc_co_u32_e32 v33, vcc, 0, v33, vcc
	global_load_dword v34, v[34:35], off nt
	s_nop 0
	global_load_dword v35, v[36:37], off nt
	s_nop 0
	global_load_dword v36, v[38:39], off nt
	global_load_dword v37, v[40:41], off nt
	s_nop 0
	global_load_dword v38, v[42:43], off nt
	global_load_dword v39, v[44:45], off nt
	global_load_dword v40, v[46:47], off nt
	s_nop 0
	global_load_dword v32, v[32:33], off nt
	s_waitcnt vmcnt(30)
	ds_write2_b32 v18, v0, v31 offset1:66
	s_waitcnt vmcnt(28)
	ds_write2_b32 v18, v50, v51 offset0:132 offset1:198
	s_waitcnt vmcnt(26)
	ds_write2_b32 v24, v52, v53 offset0:8 offset1:74
	s_waitcnt vmcnt(24)
	ds_write2_b32 v24, v54, v55 offset0:140 offset1:206
	s_waitcnt vmcnt(22)
	ds_write2_b32 v25, v56, v57 offset0:16 offset1:82
	s_waitcnt vmcnt(20)
	ds_write2_b32 v25, v58, v59 offset0:148 offset1:214
	s_waitcnt vmcnt(18)
	ds_write2_b32 v26, v60, v61 offset0:24 offset1:90
	s_waitcnt vmcnt(16)
	ds_write2_b32 v26, v62, v63 offset0:156 offset1:222
	s_waitcnt vmcnt(14)
	ds_write2_b32 v27, v64, v65 offset0:32 offset1:98
	s_waitcnt vmcnt(12)
	ds_write2_b32 v27, v66, v67 offset0:164 offset1:230
	s_waitcnt vmcnt(10)
	ds_write2_b32 v28, v68, v69 offset0:40 offset1:106
	s_waitcnt vmcnt(8)
	ds_write2_b32 v28, v70, v48 offset0:172 offset1:238
	s_waitcnt vmcnt(6)
	ds_write2_b32 v29, v34, v35 offset0:48 offset1:114
	s_waitcnt vmcnt(4)
	ds_write2_b32 v29, v36, v37 offset0:180 offset1:246
	s_waitcnt vmcnt(2)
	ds_write2_b32 v30, v38, v39 offset0:56 offset1:122
	s_waitcnt vmcnt(0)
	ds_write2_b32 v30, v40, v32 offset0:188 offset1:254
	s_waitcnt lgkmcnt(0)
	ds_read2_b32 v[36:37], v20 offset0:33 offset1:41
	ds_read2_b32 v[38:39], v20 offset1:8
	ds_read2_b32 v[40:41], v20 offset0:66 offset1:74
	ds_read2_b32 v[42:43], v20 offset0:99 offset1:107
	ds_read2_b32 v[44:45], v20 offset0:132 offset1:140
	ds_read2_b32 v[46:47], v20 offset0:165 offset1:173
	ds_read2_b32 v[48:49], v20 offset0:198 offset1:206
	ds_read2_b32 v[50:51], v20 offset0:231 offset1:239
	v_lshl_add_u64 v[52:53], v[8:9], 0, s[0:1]
	v_lshlrev_b32_e32 v0, 11, v17
	s_waitcnt lgkmcnt(6)
	v_cvt_pk_bf16_f32 v32, v38, v36
	s_waitcnt lgkmcnt(4)
	v_cvt_pk_bf16_f32 v33, v40, v42
	s_waitcnt lgkmcnt(2)
	v_cvt_pk_bf16_f32 v34, v44, v46
	s_waitcnt lgkmcnt(0)
	v_cvt_pk_bf16_f32 v35, v48, v50
	v_lshl_add_u64 v[54:55], v[52:53], 0, v[0:1]
	global_store_dwordx4 v[54:55], v[32:35], off
	v_lshlrev_b32_e32 v0, 11, v16
	v_lshl_add_u64 v[16:17], v[52:53], 0, v[0:1]
	v_cvt_pk_bf16_f32 v32, v39, v37
	v_cvt_pk_bf16_f32 v33, v41, v43
	v_cvt_pk_bf16_f32 v34, v45, v47
	v_cvt_pk_bf16_f32 v35, v49, v51
	ds_read2_b32 v[36:37], v20 offset0:49 offset1:57
	ds_read2_b32 v[38:39], v20 offset0:16 offset1:24
	ds_read2_b32 v[40:41], v20 offset0:82 offset1:90
	ds_read2_b32 v[42:43], v20 offset0:115 offset1:123
	ds_read2_b32 v[44:45], v20 offset0:148 offset1:156
	ds_read2_b32 v[46:47], v20 offset0:181 offset1:189
	ds_read2_b32 v[48:49], v20 offset0:214 offset1:222
	ds_read2_b32 v[50:51], v20 offset0:247 offset1:255
	v_lshlrev_b32_e32 v0, 11, v15
	global_store_dwordx4 v[16:17], v[32:35], off
	v_lshl_add_u64 v[16:17], v[52:53], 0, v[0:1]
	v_lshlrev_b32_e32 v0, 11, v14
	s_waitcnt lgkmcnt(6)
	v_cvt_pk_bf16_f32 v32, v38, v36
	s_waitcnt lgkmcnt(4)
	v_cvt_pk_bf16_f32 v33, v40, v42
	s_waitcnt lgkmcnt(2)
	v_cvt_pk_bf16_f32 v34, v44, v46
	s_waitcnt lgkmcnt(0)
	v_cvt_pk_bf16_f32 v35, v48, v50
	global_store_dwordx4 v[16:17], v[32:35], off
	v_lshl_add_u64 v[14:15], v[52:53], 0, v[0:1]
	s_nop 0
	v_cvt_pk_bf16_f32 v32, v39, v37
	v_cvt_pk_bf16_f32 v33, v41, v43
	v_cvt_pk_bf16_f32 v34, v45, v47
	v_cvt_pk_bf16_f32 v35, v49, v51
	global_store_dwordx4 v[14:15], v[32:35], off
	s_waitcnt lgkmcnt(0)

.LBB0_842:
	s_andn2_b64 vcc, exec, s[4:5]
	s_cbranch_vccnz .LBB0_835
	s_ashr_i32 s0, s8, 31
	s_lshr_b32 s0, s0, 25
	s_add_i32 s0, s8, s0
	s_ashr_i32 s0, s0, 7
	s_lshl_b32 s6, s0, 6
	s_lshl_b32 s0, s0, 12
	s_sub_i32 s4, s10, s0
	v_or_b32_e32 v16, s6, v229
	s_ashr_i32 s5, s4, 31
	v_ashrrev_i32_e32 v17, 31, v16
	v_lshl_add_u64 v[14:15], s[4:5], 2, v[10:11]
	v_lshlrev_b64 v[32:33], 14, v[16:17]
	v_lshl_add_u64 v[32:33], v[14:15], 0, v[32:33]
	global_load_dword v0, v[32:33], off nt
	v_lshl_add_u64 v[32:33], v[16:17], 2, s[2:3]
	global_load_dword v31, v[32:33], off nt
	v_or_b32_e32 v32, 2, v16
	v_ashrrev_i32_e32 v33, 31, v32
	v_lshlrev_b64 v[34:35], 14, v[32:33]
	v_lshl_add_u64 v[32:33], v[32:33], 2, s[2:3]
	global_load_dword v37, v[32:33], off nt
	v_or_b32_e32 v32, 4, v16
	v_lshl_add_u64 v[34:35], v[14:15], 0, v[34:35]
	v_ashrrev_i32_e32 v33, 31, v32
	global_load_dword v36, v[34:35], off nt
	v_lshlrev_b64 v[34:35], 14, v[32:33]
	v_lshl_add_u64 v[32:33], v[32:33], 2, s[2:3]
	global_load_dword v39, v[32:33], off nt
	v_or_b32_e32 v32, 6, v16
	v_lshl_add_u64 v[34:35], v[14:15], 0, v[34:35]
	v_ashrrev_i32_e32 v33, 31, v32
	global_load_dword v38, v[34:35], off nt
	v_lshlrev_b64 v[34:35], 14, v[32:33]
	v_lshl_add_u64 v[32:33], v[32:33], 2, s[2:3]
	global_load_dword v41, v[32:33], off nt
	v_or_b32_e32 v32, 8, v16
	v_lshl_add_u64 v[34:35], v[14:15], 0, v[34:35]
	v_ashrrev_i32_e32 v33, 31, v32
	global_load_dword v40, v[34:35], off nt
	v_lshlrev_b64 v[34:35], 14, v[32:33]
	v_lshl_add_u64 v[32:33], v[32:33], 2, s[2:3]
	global_load_dword v43, v[32:33], off nt
	v_or_b32_e32 v32, 10, v16
	v_lshl_add_u64 v[34:35], v[14:15], 0, v[34:35]
	v_ashrrev_i32_e32 v33, 31, v32
	global_load_dword v42, v[34:35], off nt
	v_lshlrev_b64 v[34:35], 14, v[32:33]
	v_lshl_add_u64 v[32:33], v[32:33], 2, s[2:3]
	global_load_dword v45, v[32:33], off nt
	v_or_b32_e32 v32, 12, v16
	v_lshl_add_u64 v[34:35], v[14:15], 0, v[34:35]
	v_ashrrev_i32_e32 v33, 31, v32
	global_load_dword v44, v[34:35], off nt
	v_lshlrev_b64 v[34:35], 14, v[32:33]
	v_lshl_add_u64 v[32:33], v[32:33], 2, s[2:3]
	global_load_dword v47, v[32:33], off nt
	v_or_b32_e32 v32, 14, v16
	v_lshl_add_u64 v[34:35], v[14:15], 0, v[34:35]
	v_ashrrev_i32_e32 v33, 31, v32
	global_load_dword v46, v[34:35], off nt
	v_lshlrev_b64 v[34:35], 14, v[32:33]
	v_lshl_add_u64 v[32:33], v[32:33], 2, s[2:3]
	global_load_dword v49, v[32:33], off nt
	v_or_b32_e32 v32, 16, v16
	v_lshl_add_u64 v[34:35], v[14:15], 0, v[34:35]
	v_ashrrev_i32_e32 v33, 31, v32
	global_load_dword v48, v[34:35], off nt
	v_lshlrev_b64 v[34:35], 14, v[32:33]
	v_lshl_add_u64 v[32:33], v[32:33], 2, s[2:3]
	global_load_dword v51, v[32:33], off nt
	v_or_b32_e32 v32, 18, v16
	v_lshl_add_u64 v[34:35], v[14:15], 0, v[34:35]
	v_ashrrev_i32_e32 v33, 31, v32
	global_load_dword v50, v[34:35], off nt
	v_lshlrev_b64 v[34:35], 14, v[32:33]
	v_lshl_add_u64 v[32:33], v[32:33], 2, s[2:3]
	global_load_dword v53, v[32:33], off nt
	v_or_b32_e32 v32, 20, v16
	v_lshl_add_u64 v[34:35], v[14:15], 0, v[34:35]
	v_ashrrev_i32_e32 v33, 31, v32
	global_load_dword v52, v[34:35], off nt
	v_lshlrev_b64 v[34:35], 14, v[32:33]
	v_lshl_add_u64 v[32:33], v[32:33], 2, s[2:3]
	global_load_dword v55, v[32:33], off nt
	v_or_b32_e32 v32, 22, v16
	v_lshl_add_u64 v[34:35], v[14:15], 0, v[34:35]
	v_ashrrev_i32_e32 v33, 31, v32
	global_load_dword v54, v[34:35], off nt
	v_lshlrev_b64 v[34:35], 14, v[32:33]
	v_lshl_add_u64 v[32:33], v[32:33], 2, s[2:3]
	global_load_dword v57, v[32:33], off nt
	v_or_b32_e32 v32, 24, v16
	v_lshl_add_u64 v[34:35], v[14:15], 0, v[34:35]
	v_ashrrev_i32_e32 v33, 31, v32
	global_load_dword v56, v[34:35], off nt
	v_lshlrev_b64 v[34:35], 14, v[32:33]
	v_lshl_add_u64 v[32:33], v[32:33], 2, s[2:3]
	global_load_dword v59, v[32:33], off nt
	v_or_b32_e32 v32, 26, v16
	v_lshl_add_u64 v[34:35], v[14:15], 0, v[34:35]
	v_ashrrev_i32_e32 v33, 31, v32
	global_load_dword v58, v[34:35], off nt
	v_lshlrev_b64 v[34:35], 14, v[32:33]
	v_lshl_add_u64 v[32:33], v[32:33], 2, s[2:3]
	global_load_dword v61, v[32:33], off nt
	v_or_b32_e32 v32, 28, v16
	v_lshl_add_u64 v[34:35], v[14:15], 0, v[34:35]
	v_ashrrev_i32_e32 v33, 31, v32
	global_load_dword v60, v[34:35], off nt
	v_lshlrev_b64 v[34:35], 14, v[32:33]
	v_lshl_add_u64 v[32:33], v[32:33], 2, s[2:3]
	global_load_dword v63, v[32:33], off nt
	v_or_b32_e32 v32, 30, v16
	v_lshl_add_u64 v[34:35], v[14:15], 0, v[34:35]
	v_ashrrev_i32_e32 v33, 31, v32
	global_load_dword v62, v[34:35], off nt
	v_lshlrev_b64 v[34:35], 14, v[32:33]
	v_lshl_add_u64 v[32:33], v[32:33], 2, s[2:3]
	global_load_dword v65, v[32:33], off nt
	v_or_b32_e32 v32, 32, v16
	v_lshl_add_u64 v[34:35], v[14:15], 0, v[34:35]
	v_ashrrev_i32_e32 v33, 31, v32
	global_load_dword v64, v[34:35], off nt
	v_lshlrev_b64 v[34:35], 14, v[32:33]
	v_lshl_add_u64 v[32:33], v[32:33], 2, s[2:3]
	global_load_dword v67, v[32:33], off nt
	v_or_b32_e32 v32, 34, v16
	v_lshl_add_u64 v[34:35], v[14:15], 0, v[34:35]
	v_ashrrev_i32_e32 v33, 31, v32
	global_load_dword v66, v[34:35], off nt
	v_lshlrev_b64 v[34:35], 14, v[32:33]
	v_lshl_add_u64 v[32:33], v[32:33], 2, s[2:3]
	global_load_dword v69, v[32:33], off nt
	v_or_b32_e32 v32, 36, v16
	v_lshl_add_u64 v[34:35], v[14:15], 0, v[34:35]
	v_ashrrev_i32_e32 v33, 31, v32
	global_load_dword v68, v[34:35], off nt
	v_lshlrev_b64 v[34:35], 14, v[32:33]
	v_lshl_add_u64 v[32:33], v[32:33], 2, s[2:3]
	global_load_dword v71, v[32:33], off nt
	v_or_b32_e32 v32, 38, v16
	v_lshl_add_u64 v[34:35], v[14:15], 0, v[34:35]
	v_ashrrev_i32_e32 v33, 31, v32
	global_load_dword v70, v[34:35], off nt
	v_lshlrev_b64 v[34:35], 14, v[32:33]
	v_lshl_add_u64 v[32:33], v[32:33], 2, s[2:3]
	global_load_dword v73, v[32:33], off nt
	v_or_b32_e32 v32, 40, v16
	v_lshl_add_u64 v[34:35], v[14:15], 0, v[34:35]
	v_ashrrev_i32_e32 v33, 31, v32
	global_load_dword v72, v[34:35], off nt
	v_lshlrev_b64 v[34:35], 14, v[32:33]
	v_lshl_add_u64 v[32:33], v[32:33], 2, s[2:3]
	global_load_dword v75, v[32:33], off nt
	v_or_b32_e32 v32, 42, v16
	v_lshl_add_u64 v[34:35], v[14:15], 0, v[34:35]
	v_ashrrev_i32_e32 v33, 31, v32
	global_load_dword v74, v[34:35], off nt
	v_lshlrev_b64 v[34:35], 14, v[32:33]
	v_lshl_add_u64 v[32:33], v[32:33], 2, s[2:3]
	global_load_dword v77, v[32:33], off nt
	v_or_b32_e32 v32, 44, v16
	v_lshl_add_u64 v[34:35], v[14:15], 0, v[34:35]
	v_ashrrev_i32_e32 v33, 31, v32
	global_load_dword v76, v[34:35], off nt
	v_lshlrev_b64 v[34:35], 14, v[32:33]
	v_lshl_add_u64 v[32:33], v[32:33], 2, s[2:3]
	global_load_dword v79, v[32:33], off nt
	v_or_b32_e32 v32, 46, v16
	v_lshl_add_u64 v[34:35], v[14:15], 0, v[34:35]
	v_ashrrev_i32_e32 v33, 31, v32
	global_load_dword v78, v[34:35], off nt
	v_lshlrev_b64 v[34:35], 14, v[32:33]
	v_lshl_add_u64 v[32:33], v[32:33], 2, s[2:3]
	global_load_dword v81, v[32:33], off nt
	v_or_b32_e32 v32, 48, v16
	v_lshl_add_u64 v[34:35], v[14:15], 0, v[34:35]
	v_ashrrev_i32_e32 v33, 31, v32
	global_load_dword v80, v[34:35], off nt
	v_lshlrev_b64 v[34:35], 14, v[32:33]
	v_lshl_add_u64 v[32:33], v[32:33], 2, s[2:3]
	global_load_dword v83, v[32:33], off nt
	v_or_b32_e32 v32, 50, v16
	v_lshl_add_u64 v[34:35], v[14:15], 0, v[34:35]
	v_ashrrev_i32_e32 v33, 31, v32
	global_load_dword v82, v[34:35], off nt
	v_lshlrev_b64 v[34:35], 14, v[32:33]
	v_lshl_add_u64 v[32:33], v[32:33], 2, s[2:3]
	global_load_dword v85, v[32:33], off nt
	v_or_b32_e32 v32, 52, v16
	v_lshl_add_u64 v[34:35], v[14:15], 0, v[34:35]
	v_ashrrev_i32_e32 v33, 31, v32
	global_load_dword v84, v[34:35], off nt
	v_lshlrev_b64 v[34:35], 14, v[32:33]
	v_lshl_add_u64 v[32:33], v[32:33], 2, s[2:3]
	global_load_dword v87, v[32:33], off nt
	v_or_b32_e32 v32, 54, v16
	v_lshl_add_u64 v[34:35], v[14:15], 0, v[34:35]
	v_ashrrev_i32_e32 v33, 31, v32
	global_load_dword v86, v[34:35], off nt
	v_lshlrev_b64 v[34:35], 14, v[32:33]
	v_lshl_add_u64 v[32:33], v[32:33], 2, s[2:3]
	global_load_dword v89, v[32:33], off nt
	v_or_b32_e32 v32, 56, v16
	v_lshl_add_u64 v[34:35], v[14:15], 0, v[34:35]
	v_ashrrev_i32_e32 v33, 31, v32
	global_load_dword v88, v[34:35], off nt
	v_lshlrev_b64 v[34:35], 14, v[32:33]
	v_lshl_add_u64 v[32:33], v[32:33], 2, s[2:3]
	global_load_dword v91, v[32:33], off nt
	v_or_b32_e32 v32, 58, v16
	v_lshl_add_u64 v[34:35], v[14:15], 0, v[34:35]
	v_ashrrev_i32_e32 v33, 31, v32
	global_load_dword v90, v[34:35], off nt
	v_lshlrev_b64 v[34:35], 14, v[32:33]
	v_lshl_add_u64 v[32:33], v[32:33], 2, s[2:3]
	global_load_dword v93, v[32:33], off nt
	v_or_b32_e32 v32, 60, v16
	v_lshl_add_u64 v[34:35], v[14:15], 0, v[34:35]
	v_ashrrev_i32_e32 v33, 31, v32
	global_load_dword v92, v[34:35], off nt
	v_lshlrev_b64 v[34:35], 14, v[32:33]
	v_or_b32_e32 v16, 62, v16
	v_lshl_add_u64 v[34:35], v[14:15], 0, v[34:35]
	v_lshl_add_u64 v[32:33], v[32:33], 2, s[2:3]
	v_ashrrev_i32_e32 v17, 31, v16
	global_load_dword v34, v[34:35], off nt
	s_waitcnt vmcnt(59)
	v_mul_f32_e32 v0, v0, v31
	global_load_dword v35, v[32:33], off nt
	v_lshlrev_b64 v[32:33], 14, v[16:17]
	v_lshl_add_u64 v[14:15], v[14:15], 0, v[32:33]
	global_load_dword v32, v[14:15], off nt
	v_lshl_add_u64 v[14:15], v[16:17], 2, s[2:3]
	global_load_dword v14, v[14:15], off nt
	s_waitcnt vmcnt(60)
	v_mul_f32_e32 v15, v36, v37
	ds_write2_b32 v18, v0, v15 offset1:66
	s_waitcnt vmcnt(58)
	v_mul_f32_e32 v0, v38, v39
	s_waitcnt vmcnt(56)
	v_mul_f32_e32 v15, v40, v41
	ds_write2_b32 v18, v0, v15 offset0:132 offset1:198
	s_waitcnt vmcnt(54)
	v_mul_f32_e32 v0, v42, v43
	s_waitcnt vmcnt(52)
	v_mul_f32_e32 v15, v44, v45
	ds_write2_b32 v24, v0, v15 offset0:8 offset1:74
	s_waitcnt vmcnt(50)
	v_mul_f32_e32 v0, v46, v47
	s_waitcnt vmcnt(48)
	v_mul_f32_e32 v15, v48, v49
	ds_write2_b32 v24, v0, v15 offset0:140 offset1:206
	s_waitcnt vmcnt(46)
	v_mul_f32_e32 v0, v50, v51
	s_waitcnt vmcnt(44)
	v_mul_f32_e32 v15, v52, v53
	ds_write2_b32 v25, v0, v15 offset0:16 offset1:82
	s_waitcnt vmcnt(42)
	v_mul_f32_e32 v0, v54, v55
	s_waitcnt vmcnt(40)
	v_mul_f32_e32 v15, v56, v57
	ds_write2_b32 v25, v0, v15 offset0:148 offset1:214
	s_waitcnt vmcnt(38)
	v_mul_f32_e32 v0, v58, v59
	s_waitcnt vmcnt(36)
	v_mul_f32_e32 v15, v60, v61
	ds_write2_b32 v26, v0, v15 offset0:24 offset1:90
	s_waitcnt vmcnt(34)
	v_mul_f32_e32 v0, v62, v63
	s_waitcnt vmcnt(32)
	v_mul_f32_e32 v15, v64, v65
	ds_write2_b32 v26, v0, v15 offset0:156 offset1:222
	s_waitcnt vmcnt(30)
	v_mul_f32_e32 v0, v66, v67
	s_waitcnt vmcnt(28)
	v_mul_f32_e32 v15, v68, v69
	ds_write2_b32 v27, v0, v15 offset0:32 offset1:98
	s_waitcnt vmcnt(26)
	v_mul_f32_e32 v0, v70, v71
	s_waitcnt vmcnt(24)
	v_mul_f32_e32 v15, v72, v73
	ds_write2_b32 v27, v0, v15 offset0:164 offset1:230
	s_waitcnt vmcnt(22)
	v_mul_f32_e32 v0, v74, v75
	s_waitcnt vmcnt(20)
	v_mul_f32_e32 v15, v76, v77
	ds_write2_b32 v28, v0, v15 offset0:40 offset1:106
	s_waitcnt vmcnt(18)
	v_mul_f32_e32 v0, v78, v79
	s_waitcnt vmcnt(16)
	v_mul_f32_e32 v15, v80, v81
	ds_write2_b32 v28, v0, v15 offset0:172 offset1:238
	s_waitcnt vmcnt(14)
	v_mul_f32_e32 v0, v82, v83
	v_add_u32_e32 v50, s4, v19
	s_ashr_i32 s7, s6, 31
	s_waitcnt vmcnt(12)
	v_mul_f32_e32 v15, v84, v85
	ds_write2_b32 v29, v0, v15 offset0:48 offset1:114
	v_ashrrev_i32_e32 v51, 31, v50
	v_lshl_add_u64 v[48:49], s[6:7], 1, v[12:13]
	v_lshlrev_b64 v[52:53], 11, v[50:51]
	v_lshl_add_u64 v[52:53], v[48:49], 0, v[52:53]
	s_waitcnt vmcnt(10)
	v_mul_f32_e32 v0, v86, v87
	s_waitcnt vmcnt(8)
	v_mul_f32_e32 v15, v88, v89
	ds_write2_b32 v29, v0, v15 offset0:180 offset1:246
	s_waitcnt vmcnt(6)
	v_mul_f32_e32 v0, v90, v91
	s_waitcnt vmcnt(4)
	v_mul_f32_e32 v15, v92, v93
	ds_write2_b32 v30, v0, v15 offset0:56 offset1:122
	s_waitcnt vmcnt(2)
	v_mul_f32_e32 v0, v34, v35
	s_waitcnt vmcnt(0)
	v_mul_f32_e32 v14, v32, v14
	ds_write2_b32 v30, v0, v14 offset0:188 offset1:254
	s_waitcnt lgkmcnt(0)
	ds_read2_b32 v[32:33], v20 offset0:33 offset1:41
	ds_read2_b32 v[34:35], v20 offset1:8
	ds_read2_b32 v[36:37], v20 offset0:66 offset1:74
	ds_read2_b32 v[38:39], v20 offset0:99 offset1:107
	ds_read2_b32 v[40:41], v20 offset0:132 offset1:140
	ds_read2_b32 v[42:43], v20 offset0:165 offset1:173
	ds_read2_b32 v[44:45], v20 offset0:198 offset1:206
	ds_read2_b32 v[46:47], v20 offset0:231 offset1:239
	s_waitcnt lgkmcnt(6)
	v_cvt_pk_bf16_f32 v14, v34, v32
	s_waitcnt lgkmcnt(4)
	v_cvt_pk_bf16_f32 v15, v36, v38
	s_waitcnt lgkmcnt(2)
	v_cvt_pk_bf16_f32 v16, v40, v42
	v_add_u32_e32 v32, 8, v50
	s_waitcnt lgkmcnt(0)
	v_cvt_pk_bf16_f32 v17, v44, v46
	global_store_dwordx4 v[52:53], v[14:17], off
	s_nop 1
	v_cvt_pk_bf16_f32 v14, v35, v33
	v_ashrrev_i32_e32 v33, 31, v32
	v_cvt_pk_bf16_f32 v15, v37, v39
	v_cvt_pk_bf16_f32 v16, v41, v43
	v_cvt_pk_bf16_f32 v17, v45, v47
	v_lshlrev_b64 v[32:33], 11, v[32:33]
	ds_read2_b32 v[34:35], v20 offset0:49 offset1:57
	ds_read2_b32 v[36:37], v20 offset0:16 offset1:24
	ds_read2_b32 v[38:39], v20 offset0:82 offset1:90
	ds_read2_b32 v[40:41], v20 offset0:115 offset1:123
	ds_read2_b32 v[42:43], v20 offset0:148 offset1:156
	ds_read2_b32 v[44:45], v20 offset0:181 offset1:189
	ds_read2_b32 v[46:47], v20 offset0:214 offset1:222
	ds_read2_b32 v[52:53], v20 offset0:247 offset1:255
	v_lshl_add_u64 v[32:33], v[48:49], 0, v[32:33]
	global_store_dwordx4 v[32:33], v[14:17], off
	v_add_u32_e32 v32, 16, v50
	v_ashrrev_i32_e32 v33, 31, v32
	v_lshlrev_b64 v[32:33], 11, v[32:33]
	s_waitcnt lgkmcnt(6)
	v_cvt_pk_bf16_f32 v14, v36, v34
	s_waitcnt lgkmcnt(4)
	v_cvt_pk_bf16_f32 v15, v38, v40
	s_waitcnt lgkmcnt(2)
	v_cvt_pk_bf16_f32 v16, v42, v44
	s_waitcnt lgkmcnt(0)
	v_cvt_pk_bf16_f32 v17, v46, v52
	v_lshl_add_u64 v[32:33], v[48:49], 0, v[32:33]
	global_store_dwordx4 v[32:33], v[14:17], off
	v_add_u32_e32 v32, 24, v50
	v_ashrrev_i32_e32 v33, 31, v32
	v_lshlrev_b64 v[32:33], 11, v[32:33]
	v_cvt_pk_bf16_f32 v14, v37, v35
	v_cvt_pk_bf16_f32 v15, v39, v41
	v_cvt_pk_bf16_f32 v16, v43, v45
	v_cvt_pk_bf16_f32 v17, v47, v53
	v_lshl_add_u64 v[32:33], v[48:49], 0, v[32:33]
	global_store_dwordx4 v[32:33], v[14:17], off
	s_waitcnt lgkmcnt(0)
	s_branch .LBB0_835

.LBB0_849:
	s_cmpk_gt_i32 s8, 0x7ff
	s_mov_b64 s[4:5], -1
	s_cbranch_scc0 .LBB0_855
	s_and_b32 s6, s9, 0x3e0
	s_cmpk_gt_u32 s8, 0x9ff
	v_or_b32_e32 v17, s6, v19
	v_or_b32_e32 v16, s6, v21
	v_or_b32_e32 v15, s6, v22
	v_or_b32_e32 v14, s6, v23
	s_cbranch_scc0 .LBB0_852
	s_and_b32 s4, s10, 0x1ffc0
	v_or_b32_e32 v0, s4, v229
	s_lshl_b32 s0, s6, 2
	v_lshl_add_u64 v[32:33], v[4:5], 0, s[0:1]
	v_lshlrev_b32_e32 v0, 12, v0
	v_lshl_add_u64 v[32:33], v[32:33], 0, v[0:1]
	v_add_co_u32_e32 v34, vcc, 0x2000, v32
	s_lshl_b32 s0, s4, 1
	s_nop 0
	v_addc_co_u32_e32 v35, vcc, 0, v33, vcc
	v_add_co_u32_e32 v36, vcc, 0x4000, v32
	s_mov_b64 s[4:5], 0
	s_nop 0
	v_addc_co_u32_e32 v37, vcc, 0, v33, vcc
	v_add_co_u32_e32 v38, vcc, 0x6000, v32
	s_nop 1
	v_addc_co_u32_e32 v39, vcc, 0, v33, vcc
	v_add_co_u32_e32 v40, vcc, 0x8000, v32
	s_nop 1
	v_addc_co_u32_e32 v41, vcc, 0, v33, vcc
	v_add_co_u32_e32 v42, vcc, 0xa000, v32
	s_nop 1
	v_addc_co_u32_e32 v43, vcc, 0, v33, vcc
	v_add_co_u32_e32 v44, vcc, 0xc000, v32
	s_nop 1
	v_addc_co_u32_e32 v45, vcc, 0, v33, vcc
	v_add_co_u32_e32 v46, vcc, 0xe000, v32
	s_nop 1
	v_addc_co_u32_e32 v47, vcc, 0, v33, vcc
	global_load_dword v0, v[32:33], off nt
	global_load_dword v31, v[34:35], off nt
	global_load_dword v50, v[36:37], off nt
	global_load_dword v51, v[38:39], off nt
	global_load_dword v52, v[40:41], off nt
	global_load_dword v53, v[42:43], off nt
	global_load_dword v54, v[44:45], off nt
	global_load_dword v55, v[46:47], off nt
	v_add_co_u32_e32 v34, vcc, 0x10000, v32
	s_nop 1
	v_addc_co_u32_e32 v35, vcc, 0, v33, vcc
	v_add_co_u32_e32 v36, vcc, 0x12000, v32
	s_nop 1
	v_addc_co_u32_e32 v37, vcc, 0, v33, vcc
	v_add_co_u32_e32 v38, vcc, 0x14000, v32
	s_nop 1
	v_addc_co_u32_e32 v39, vcc, 0, v33, vcc
	v_add_co_u32_e32 v40, vcc, 0x16000, v32
	s_nop 1
	v_addc_co_u32_e32 v41, vcc, 0, v33, vcc
	v_add_co_u32_e32 v42, vcc, 0x18000, v32
	s_nop 1
	v_addc_co_u32_e32 v43, vcc, 0, v33, vcc
	v_add_co_u32_e32 v44, vcc, 0x1a000, v32
	s_nop 1
	v_addc_co_u32_e32 v45, vcc, 0, v33, vcc
	v_add_co_u32_e32 v46, vcc, 0x1c000, v32
	s_nop 1
	v_addc_co_u32_e32 v47, vcc, 0, v33, vcc
	v_add_co_u32_e32 v48, vcc, 0x1e000, v32
	s_nop 1
	v_addc_co_u32_e32 v49, vcc, 0, v33, vcc
	global_load_dword v56, v[34:35], off nt
	global_load_dword v57, v[36:37], off nt
	global_load_dword v58, v[38:39], off nt
	global_load_dword v59, v[40:41], off nt
	global_load_dword v60, v[42:43], off nt
	global_load_dword v61, v[44:45], off nt
	global_load_dword v62, v[46:47], off nt
	global_load_dword v63, v[48:49], off nt
	v_add_co_u32_e32 v34, vcc, 0x20000, v32
	s_nop 1
	v_addc_co_u32_e32 v35, vcc, 0, v33, vcc
	v_add_co_u32_e32 v36, vcc, 0x22000, v32
	s_nop 1
	v_addc_co_u32_e32 v37, vcc, 0, v33, vcc
	v_add_co_u32_e32 v38, vcc, 0x24000, v32
	s_nop 1
	v_addc_co_u32_e32 v39, vcc, 0, v33, vcc
	v_add_co_u32_e32 v40, vcc, 0x26000, v32
	s_nop 1
	v_addc_co_u32_e32 v41, vcc, 0, v33, vcc
	v_add_co_u32_e32 v42, vcc, 0x28000, v32
	s_nop 1
	v_addc_co_u32_e32 v43, vcc, 0, v33, vcc
	v_add_co_u32_e32 v44, vcc, 0x2a000, v32
	s_nop 1
	v_addc_co_u32_e32 v45, vcc, 0, v33, vcc
	v_add_co_u32_e32 v46, vcc, 0x2c000, v32
	s_nop 1
	v_addc_co_u32_e32 v47, vcc, 0, v33, vcc
	v_add_co_u32_e32 v48, vcc, 0x2e000, v32
	s_nop 1
	v_addc_co_u32_e32 v49, vcc, 0, v33, vcc
	global_load_dword v64, v[34:35], off nt
	global_load_dword v65, v[36:37], off nt
	global_load_dword v66, v[38:39], off nt
	global_load_dword v67, v[40:41], off nt
	global_load_dword v68, v[42:43], off nt
	global_load_dword v69, v[44:45], off nt
	global_load_dword v70, v[46:47], off nt
	global_load_dword v71, v[48:49], off nt
	v_add_co_u32_e32 v34, vcc, 0x30000, v32
	s_nop 1
	v_addc_co_u32_e32 v35, vcc, 0, v33, vcc
	v_add_co_u32_e32 v36, vcc, 0x32000, v32
	s_nop 1
	v_addc_co_u32_e32 v37, vcc, 0, v33, vcc
	v_add_co_u32_e32 v38, vcc, 0x34000, v32
	s_nop 1
	v_addc_co_u32_e32 v39, vcc, 0, v33, vcc
	v_add_co_u32_e32 v40, vcc, 0x36000, v32
	s_nop 1
	v_addc_co_u32_e32 v41, vcc, 0, v33, vcc
	v_add_co_u32_e32 v42, vcc, 0x38000, v32
	s_nop 1
	v_addc_co_u32_e32 v43, vcc, 0, v33, vcc
	v_add_co_u32_e32 v44, vcc, 0x3a000, v32
	s_nop 1
	v_addc_co_u32_e32 v45, vcc, 0, v33, vcc
	v_add_co_u32_e32 v46, vcc, 0x3c000, v32
	s_nop 1
	v_addc_co_u32_e32 v47, vcc, 0, v33, vcc
	v_add_co_u32_e32 v32, vcc, 0x3e000, v32
	s_nop 1
	v_addc_co_u32_e32 v33, vcc, 0, v33, vcc
	global_load_dword v48, v[34:35], off nt
	global_load_dword v49, v[36:37], off nt
	global_load_dword v72, v[38:39], off nt
	global_load_dword v73, v[40:41], off nt
	global_load_dword v74, v[42:43], off nt
	global_load_dword v75, v[44:45], off nt
	global_load_dword v76, v[46:47], off nt
	global_load_dword v77, v[32:33], off nt
	s_waitcnt vmcnt(30)
	ds_write2_b32 v18, v0, v31 offset1:66
	s_waitcnt vmcnt(28)
	ds_write2_b32 v18, v50, v51 offset0:132 offset1:198
	s_waitcnt vmcnt(26)
	ds_write2_b32 v24, v52, v53 offset0:8 offset1:74
	s_waitcnt vmcnt(24)
	ds_write2_b32 v24, v54, v55 offset0:140 offset1:206
	s_waitcnt vmcnt(22)
	ds_write2_b32 v25, v56, v57 offset0:16 offset1:82
	s_waitcnt vmcnt(20)
	ds_write2_b32 v25, v58, v59 offset0:148 offset1:214
	s_waitcnt vmcnt(18)
	ds_write2_b32 v26, v60, v61 offset0:24 offset1:90
	s_waitcnt vmcnt(16)
	ds_write2_b32 v26, v62, v63 offset0:156 offset1:222
	s_waitcnt vmcnt(14)
	ds_write2_b32 v27, v64, v65 offset0:32 offset1:98
	s_waitcnt vmcnt(12)
	ds_write2_b32 v27, v66, v67 offset0:164 offset1:230
	s_waitcnt vmcnt(10)
	ds_write2_b32 v28, v68, v69 offset0:40 offset1:106
	s_waitcnt vmcnt(8)
	ds_write2_b32 v28, v70, v71 offset0:172 offset1:238
	s_waitcnt vmcnt(6)
	ds_write2_b32 v29, v48, v49 offset0:48 offset1:114
	s_waitcnt vmcnt(4)
	ds_write2_b32 v29, v72, v73 offset0:180 offset1:246
	s_waitcnt vmcnt(2)
	ds_write2_b32 v30, v74, v75 offset0:56 offset1:122
	s_waitcnt vmcnt(0)
	ds_write2_b32 v30, v76, v77 offset0:188 offset1:254
	s_waitcnt lgkmcnt(0)
	ds_read2_b32 v[36:37], v20 offset0:33 offset1:41
	ds_read2_b32 v[38:39], v20 offset1:8
	ds_read2_b32 v[40:41], v20 offset0:66 offset1:74
	ds_read2_b32 v[42:43], v20 offset0:99 offset1:107
	ds_read2_b32 v[44:45], v20 offset0:132 offset1:140
	ds_read2_b32 v[46:47], v20 offset0:165 offset1:173
	ds_read2_b32 v[48:49], v20 offset0:198 offset1:206
	ds_read2_b32 v[50:51], v20 offset0:231 offset1:239
	v_lshl_add_u64 v[52:53], v[6:7], 0, s[0:1]
	v_lshlrev_b32_e32 v0, 13, v17
	s_waitcnt lgkmcnt(6)
	v_cvt_pk_bf16_f32 v32, v38, v36
	s_waitcnt lgkmcnt(4)
	v_cvt_pk_bf16_f32 v33, v40, v42
	s_waitcnt lgkmcnt(2)
	v_cvt_pk_bf16_f32 v34, v44, v46
	s_waitcnt lgkmcnt(0)
	v_cvt_pk_bf16_f32 v35, v48, v50
	v_lshl_add_u64 v[54:55], v[52:53], 0, v[0:1]
	global_store_dwordx4 v[54:55], v[32:35], off
	v_lshlrev_b32_e32 v0, 13, v16
	s_nop 0
	v_cvt_pk_bf16_f32 v32, v39, v37
	v_cvt_pk_bf16_f32 v33, v41, v43
	v_cvt_pk_bf16_f32 v34, v45, v47
	v_cvt_pk_bf16_f32 v35, v49, v51
	ds_read2_b32 v[38:39], v20 offset0:49 offset1:57
	ds_read2_b32 v[40:41], v20 offset0:16 offset1:24
	ds_read2_b32 v[42:43], v20 offset0:82 offset1:90
	ds_read2_b32 v[44:45], v20 offset0:115 offset1:123
	ds_read2_b32 v[46:47], v20 offset0:148 offset1:156
	ds_read2_b32 v[48:49], v20 offset0:181 offset1:189
	ds_read2_b32 v[50:51], v20 offset0:214 offset1:222
	ds_read2_b32 v[54:55], v20 offset0:247 offset1:255
	v_lshl_add_u64 v[36:37], v[52:53], 0, v[0:1]
	v_lshlrev_b32_e32 v0, 13, v15
	global_store_dwordx4 v[36:37], v[32:35], off
	v_lshl_add_u64 v[36:37], v[52:53], 0, v[0:1]
	v_lshlrev_b32_e32 v0, 13, v14
	s_waitcnt lgkmcnt(6)
	v_cvt_pk_bf16_f32 v32, v40, v38
	s_waitcnt lgkmcnt(4)
	v_cvt_pk_bf16_f32 v33, v42, v44
	s_waitcnt lgkmcnt(2)
	v_cvt_pk_bf16_f32 v34, v46, v48
	s_waitcnt lgkmcnt(0)
	v_cvt_pk_bf16_f32 v35, v50, v54
	global_store_dwordx4 v[36:37], v[32:35], off
	v_lshl_add_u64 v[36:37], v[52:53], 0, v[0:1]
	s_nop 0
	v_cvt_pk_bf16_f32 v32, v41, v39
	v_cvt_pk_bf16_f32 v33, v43, v45
	v_cvt_pk_bf16_f32 v34, v47, v49
	v_cvt_pk_bf16_f32 v35, v51, v55
	global_store_dwordx4 v[36:37], v[32:35], off
	s_waitcnt lgkmcnt(0)
.LBB0_852:
	s_andn2_b64 vcc, exec, s[4:5]
	s_cbranch_vccnz .LBB0_854
	s_add_i32 s0, s10, 0x400
	s_and_b32 s4, s0, 0x1ffc0
	v_or_b32_e32 v0, s4, v229
	s_lshl_b32 s0, s6, 2
	v_lshl_add_u64 v[32:33], v[2:3], 0, s[0:1]
	v_lshlrev_b32_e32 v0, 12, v0
	v_lshl_add_u64 v[32:33], v[32:33], 0, v[0:1]
	v_add_co_u32_e32 v34, vcc, 0x2000, v32
	s_lshl_b32 s0, s4, 1
	s_nop 0
	v_addc_co_u32_e32 v35, vcc, 0, v33, vcc
	v_add_co_u32_e32 v36, vcc, 0x4000, v32
	s_nop 1
	v_addc_co_u32_e32 v37, vcc, 0, v33, vcc
	v_add_co_u32_e32 v38, vcc, 0x6000, v32
	s_nop 1
	v_addc_co_u32_e32 v39, vcc, 0, v33, vcc
	v_add_co_u32_e32 v40, vcc, 0x8000, v32
	s_nop 1
	v_addc_co_u32_e32 v41, vcc, 0, v33, vcc
	v_add_co_u32_e32 v42, vcc, 0xa000, v32
	s_nop 1
	v_addc_co_u32_e32 v43, vcc, 0, v33, vcc
	v_add_co_u32_e32 v44, vcc, 0xc000, v32
	s_nop 1
	v_addc_co_u32_e32 v45, vcc, 0, v33, vcc
	v_add_co_u32_e32 v46, vcc, 0xe000, v32
	s_nop 1
	v_addc_co_u32_e32 v47, vcc, 0, v33, vcc
	global_load_dword v0, v[32:33], off nt
	global_load_dword v31, v[34:35], off nt
	global_load_dword v50, v[36:37], off nt
	global_load_dword v51, v[38:39], off nt
	global_load_dword v52, v[40:41], off nt
	global_load_dword v53, v[42:43], off nt
	global_load_dword v54, v[44:45], off nt
	global_load_dword v55, v[46:47], off nt
	v_add_co_u32_e32 v34, vcc, 0x10000, v32
	s_nop 1
	v_addc_co_u32_e32 v35, vcc, 0, v33, vcc
	v_add_co_u32_e32 v36, vcc, 0x12000, v32
	s_nop 1
	v_addc_co_u32_e32 v37, vcc, 0, v33, vcc
	v_add_co_u32_e32 v38, vcc, 0x14000, v32
	s_nop 1
	v_addc_co_u32_e32 v39, vcc, 0, v33, vcc
	v_add_co_u32_e32 v40, vcc, 0x16000, v32
	s_nop 1
	v_addc_co_u32_e32 v41, vcc, 0, v33, vcc
	v_add_co_u32_e32 v42, vcc, 0x18000, v32
	s_nop 1
	v_addc_co_u32_e32 v43, vcc, 0, v33, vcc
	v_add_co_u32_e32 v44, vcc, 0x1a000, v32
	s_nop 1
	v_addc_co_u32_e32 v45, vcc, 0, v33, vcc
	v_add_co_u32_e32 v46, vcc, 0x1c000, v32
	s_nop 1
	v_addc_co_u32_e32 v47, vcc, 0, v33, vcc
	v_add_co_u32_e32 v48, vcc, 0x1e000, v32
	s_nop 1
	v_addc_co_u32_e32 v49, vcc, 0, v33, vcc
	global_load_dword v56, v[34:35], off nt
	global_load_dword v57, v[36:37], off nt
	global_load_dword v58, v[38:39], off nt
	global_load_dword v59, v[40:41], off nt
	global_load_dword v60, v[42:43], off nt
	global_load_dword v61, v[44:45], off nt
	global_load_dword v62, v[46:47], off nt
	global_load_dword v63, v[48:49], off nt
	v_add_co_u32_e32 v34, vcc, 0x20000, v32
	s_nop 1
	v_addc_co_u32_e32 v35, vcc, 0, v33, vcc
	v_add_co_u32_e32 v36, vcc, 0x22000, v32
	s_nop 1
	v_addc_co_u32_e32 v37, vcc, 0, v33, vcc
	v_add_co_u32_e32 v38, vcc, 0x24000, v32
	s_nop 1
	v_addc_co_u32_e32 v39, vcc, 0, v33, vcc
	v_add_co_u32_e32 v40, vcc, 0x26000, v32
	s_nop 1
	v_addc_co_u32_e32 v41, vcc, 0, v33, vcc
	v_add_co_u32_e32 v42, vcc, 0x28000, v32
	s_nop 1
	v_addc_co_u32_e32 v43, vcc, 0, v33, vcc
	v_add_co_u32_e32 v44, vcc, 0x2a000, v32
	s_nop 1
	v_addc_co_u32_e32 v45, vcc, 0, v33, vcc
	v_add_co_u32_e32 v46, vcc, 0x2c000, v32
	s_nop 1
	v_addc_co_u32_e32 v47, vcc, 0, v33, vcc
	v_add_co_u32_e32 v48, vcc, 0x2e000, v32
	s_nop 1
	v_addc_co_u32_e32 v49, vcc, 0, v33, vcc
	global_load_dword v64, v[34:35], off nt
	global_load_dword v65, v[36:37], off nt
	global_load_dword v66, v[38:39], off nt
	global_load_dword v67, v[40:41], off nt
	global_load_dword v68, v[42:43], off nt
	global_load_dword v69, v[44:45], off nt
	global_load_dword v70, v[46:47], off nt
	global_load_dword v71, v[48:49], off nt
	v_add_co_u32_e32 v34, vcc, 0x30000, v32
	s_nop 1
	v_addc_co_u32_e32 v35, vcc, 0, v33, vcc
	v_add_co_u32_e32 v36, vcc, 0x32000, v32
	s_nop 1
	v_addc_co_u32_e32 v37, vcc, 0, v33, vcc
	v_add_co_u32_e32 v38, vcc, 0x34000, v32
	s_nop 1
	v_addc_co_u32_e32 v39, vcc, 0, v33, vcc
	v_add_co_u32_e32 v40, vcc, 0x36000, v32
	s_nop 1
	v_addc_co_u32_e32 v41, vcc, 0, v33, vcc
	v_add_co_u32_e32 v42, vcc, 0x38000, v32
	s_nop 1
	v_addc_co_u32_e32 v43, vcc, 0, v33, vcc
	v_add_co_u32_e32 v44, vcc, 0x3a000, v32
	s_nop 1
	v_addc_co_u32_e32 v45, vcc, 0, v33, vcc
	v_add_co_u32_e32 v46, vcc, 0x3c000, v32
	s_nop 1
	v_addc_co_u32_e32 v47, vcc, 0, v33, vcc
	v_add_co_u32_e32 v32, vcc, 0x3e000, v32
	s_nop 1
	v_addc_co_u32_e32 v33, vcc, 0, v33, vcc
	global_load_dword v48, v[34:35], off nt
	global_load_dword v49, v[36:37], off nt
	global_load_dword v72, v[38:39], off nt
	global_load_dword v73, v[40:41], off nt
	global_load_dword v74, v[42:43], off nt
	global_load_dword v75, v[44:45], off nt
	global_load_dword v76, v[46:47], off nt
	global_load_dword v77, v[32:33], off nt
	s_waitcnt vmcnt(30)
	ds_write2_b32 v18, v0, v31 offset1:66
	s_waitcnt vmcnt(28)
	ds_write2_b32 v18, v50, v51 offset0:132 offset1:198
	s_waitcnt vmcnt(26)
	ds_write2_b32 v24, v52, v53 offset0:8 offset1:74
	s_waitcnt vmcnt(24)
	ds_write2_b32 v24, v54, v55 offset0:140 offset1:206
	s_waitcnt vmcnt(22)
	ds_write2_b32 v25, v56, v57 offset0:16 offset1:82
	s_waitcnt vmcnt(20)
	ds_write2_b32 v25, v58, v59 offset0:148 offset1:214
	s_waitcnt vmcnt(18)
	ds_write2_b32 v26, v60, v61 offset0:24 offset1:90
	s_waitcnt vmcnt(16)
	ds_write2_b32 v26, v62, v63 offset0:156 offset1:222
	s_waitcnt vmcnt(14)
	ds_write2_b32 v27, v64, v65 offset0:32 offset1:98
	s_waitcnt vmcnt(12)
	ds_write2_b32 v27, v66, v67 offset0:164 offset1:230
	s_waitcnt vmcnt(10)
	ds_write2_b32 v28, v68, v69 offset0:40 offset1:106
	s_waitcnt vmcnt(8)
	ds_write2_b32 v28, v70, v71 offset0:172 offset1:238
	s_waitcnt vmcnt(6)
	ds_write2_b32 v29, v48, v49 offset0:48 offset1:114
	s_waitcnt vmcnt(4)
	ds_write2_b32 v29, v72, v73 offset0:180 offset1:246
	s_waitcnt vmcnt(2)
	ds_write2_b32 v30, v74, v75 offset0:56 offset1:122
	s_waitcnt vmcnt(0)
	ds_write2_b32 v30, v76, v77 offset0:188 offset1:254
	s_waitcnt lgkmcnt(0)
	ds_read2_b32 v[36:37], v20 offset0:33 offset1:41
	ds_read2_b32 v[38:39], v20 offset1:8
	ds_read2_b32 v[40:41], v20 offset0:66 offset1:74
	ds_read2_b32 v[42:43], v20 offset0:99 offset1:107
	ds_read2_b32 v[44:45], v20 offset0:132 offset1:140
	ds_read2_b32 v[46:47], v20 offset0:165 offset1:173
	ds_read2_b32 v[48:49], v20 offset0:198 offset1:206
	ds_read2_b32 v[50:51], v20 offset0:231 offset1:239
	v_lshl_add_u64 v[52:53], v[8:9], 0, s[0:1]
	v_lshlrev_b32_e32 v0, 11, v17
	s_waitcnt lgkmcnt(6)
	v_cvt_pk_bf16_f32 v32, v38, v36
	s_waitcnt lgkmcnt(4)
	v_cvt_pk_bf16_f32 v33, v40, v42
	s_waitcnt lgkmcnt(2)
	v_cvt_pk_bf16_f32 v34, v44, v46
	s_waitcnt lgkmcnt(0)
	v_cvt_pk_bf16_f32 v35, v48, v50
	v_lshl_add_u64 v[54:55], v[52:53], 0, v[0:1]
	global_store_dwordx4 v[54:55], v[32:35], off
	v_lshlrev_b32_e32 v0, 11, v16
	v_lshl_add_u64 v[16:17], v[52:53], 0, v[0:1]
	v_cvt_pk_bf16_f32 v32, v39, v37
	v_cvt_pk_bf16_f32 v33, v41, v43
	v_cvt_pk_bf16_f32 v34, v45, v47
	v_cvt_pk_bf16_f32 v35, v49, v51
	ds_read2_b32 v[36:37], v20 offset0:49 offset1:57
	ds_read2_b32 v[38:39], v20 offset0:16 offset1:24
	ds_read2_b32 v[40:41], v20 offset0:82 offset1:90
	ds_read2_b32 v[42:43], v20 offset0:115 offset1:123
	ds_read2_b32 v[44:45], v20 offset0:148 offset1:156
	ds_read2_b32 v[46:47], v20 offset0:181 offset1:189
	ds_read2_b32 v[48:49], v20 offset0:214 offset1:222
	ds_read2_b32 v[50:51], v20 offset0:247 offset1:255
	v_lshlrev_b32_e32 v0, 11, v15
	global_store_dwordx4 v[16:17], v[32:35], off
	v_lshl_add_u64 v[16:17], v[52:53], 0, v[0:1]
	v_lshlrev_b32_e32 v0, 11, v14
	s_waitcnt lgkmcnt(6)
	v_cvt_pk_bf16_f32 v32, v38, v36
	s_waitcnt lgkmcnt(4)
	v_cvt_pk_bf16_f32 v33, v40, v42
	s_waitcnt lgkmcnt(2)
	v_cvt_pk_bf16_f32 v34, v44, v46
	s_waitcnt lgkmcnt(0)
	v_cvt_pk_bf16_f32 v35, v48, v50
	global_store_dwordx4 v[16:17], v[32:35], off
	v_lshl_add_u64 v[14:15], v[52:53], 0, v[0:1]
	s_nop 0
	v_cvt_pk_bf16_f32 v32, v39, v37
	v_cvt_pk_bf16_f32 v33, v41, v43
	v_cvt_pk_bf16_f32 v34, v45, v47
	v_cvt_pk_bf16_f32 v35, v49, v51
	global_store_dwordx4 v[14:15], v[32:35], off
	s_waitcnt lgkmcnt(0)

.LBB0_855:
	s_andn2_b64 vcc, exec, s[4:5]
	s_cbranch_vccnz .LBB0_848
	s_ashr_i32 s0, s8, 31
	s_lshr_b32 s0, s0, 25
	s_add_i32 s0, s8, s0
	s_ashr_i32 s0, s0, 7
	s_lshl_b32 s6, s0, 6
	s_lshl_b32 s0, s0, 12
	s_sub_i32 s4, s9, s0
	v_or_b32_e32 v16, s6, v229
	s_ashr_i32 s5, s4, 31
	v_ashrrev_i32_e32 v17, 31, v16
	v_lshl_add_u64 v[14:15], s[4:5], 2, v[10:11]
	v_lshlrev_b64 v[32:33], 14, v[16:17]
	v_lshl_add_u64 v[32:33], v[14:15], 0, v[32:33]
	global_load_dword v0, v[32:33], off nt
	v_lshl_add_u64 v[32:33], v[16:17], 2, s[2:3]
	global_load_dword v31, v[32:33], off nt
	v_or_b32_e32 v32, 2, v16
	v_ashrrev_i32_e32 v33, 31, v32
	v_lshlrev_b64 v[34:35], 14, v[32:33]
	v_lshl_add_u64 v[32:33], v[32:33], 2, s[2:3]
	global_load_dword v37, v[32:33], off nt
	v_or_b32_e32 v32, 4, v16
	v_lshl_add_u64 v[34:35], v[14:15], 0, v[34:35]
	v_ashrrev_i32_e32 v33, 31, v32
	global_load_dword v36, v[34:35], off nt
	v_lshlrev_b64 v[34:35], 14, v[32:33]
	v_lshl_add_u64 v[32:33], v[32:33], 2, s[2:3]
	global_load_dword v39, v[32:33], off nt
	v_or_b32_e32 v32, 6, v16
	v_lshl_add_u64 v[34:35], v[14:15], 0, v[34:35]
	v_ashrrev_i32_e32 v33, 31, v32
	global_load_dword v38, v[34:35], off nt
	v_lshlrev_b64 v[34:35], 14, v[32:33]
	v_lshl_add_u64 v[32:33], v[32:33], 2, s[2:3]
	global_load_dword v41, v[32:33], off nt
	v_or_b32_e32 v32, 8, v16
	v_lshl_add_u64 v[34:35], v[14:15], 0, v[34:35]
	v_ashrrev_i32_e32 v33, 31, v32
	global_load_dword v40, v[34:35], off nt
	v_lshlrev_b64 v[34:35], 14, v[32:33]
	v_lshl_add_u64 v[32:33], v[32:33], 2, s[2:3]
	global_load_dword v43, v[32:33], off nt
	v_or_b32_e32 v32, 10, v16
	v_lshl_add_u64 v[34:35], v[14:15], 0, v[34:35]
	v_ashrrev_i32_e32 v33, 31, v32
	global_load_dword v42, v[34:35], off nt
	v_lshlrev_b64 v[34:35], 14, v[32:33]
	v_lshl_add_u64 v[32:33], v[32:33], 2, s[2:3]
	global_load_dword v45, v[32:33], off nt
	v_or_b32_e32 v32, 12, v16
	v_lshl_add_u64 v[34:35], v[14:15], 0, v[34:35]
	v_ashrrev_i32_e32 v33, 31, v32
	global_load_dword v44, v[34:35], off nt
	v_lshlrev_b64 v[34:35], 14, v[32:33]
	v_lshl_add_u64 v[32:33], v[32:33], 2, s[2:3]
	global_load_dword v47, v[32:33], off nt
	v_or_b32_e32 v32, 14, v16
	v_lshl_add_u64 v[34:35], v[14:15], 0, v[34:35]
	v_ashrrev_i32_e32 v33, 31, v32
	global_load_dword v46, v[34:35], off nt
	v_lshlrev_b64 v[34:35], 14, v[32:33]
	v_lshl_add_u64 v[32:33], v[32:33], 2, s[2:3]
	global_load_dword v49, v[32:33], off nt
	v_or_b32_e32 v32, 16, v16
	v_lshl_add_u64 v[34:35], v[14:15], 0, v[34:35]
	v_ashrrev_i32_e32 v33, 31, v32
	global_load_dword v48, v[34:35], off nt
	v_lshlrev_b64 v[34:35], 14, v[32:33]
	v_lshl_add_u64 v[32:33], v[32:33], 2, s[2:3]
	global_load_dword v51, v[32:33], off nt
	v_or_b32_e32 v32, 18, v16
	v_lshl_add_u64 v[34:35], v[14:15], 0, v[34:35]
	v_ashrrev_i32_e32 v33, 31, v32
	global_load_dword v50, v[34:35], off nt
	v_lshlrev_b64 v[34:35], 14, v[32:33]
	v_lshl_add_u64 v[32:33], v[32:33], 2, s[2:3]
	global_load_dword v53, v[32:33], off nt
	v_or_b32_e32 v32, 20, v16
	v_lshl_add_u64 v[34:35], v[14:15], 0, v[34:35]
	v_ashrrev_i32_e32 v33, 31, v32
	global_load_dword v52, v[34:35], off nt
	v_lshlrev_b64 v[34:35], 14, v[32:33]
	v_lshl_add_u64 v[32:33], v[32:33], 2, s[2:3]
	global_load_dword v55, v[32:33], off nt
	v_or_b32_e32 v32, 22, v16
	v_lshl_add_u64 v[34:35], v[14:15], 0, v[34:35]
	v_ashrrev_i32_e32 v33, 31, v32
	global_load_dword v54, v[34:35], off nt
	v_lshlrev_b64 v[34:35], 14, v[32:33]
	v_lshl_add_u64 v[32:33], v[32:33], 2, s[2:3]
	global_load_dword v57, v[32:33], off nt
	v_or_b32_e32 v32, 24, v16
	v_lshl_add_u64 v[34:35], v[14:15], 0, v[34:35]
	v_ashrrev_i32_e32 v33, 31, v32
	global_load_dword v56, v[34:35], off nt
	v_lshlrev_b64 v[34:35], 14, v[32:33]
	v_lshl_add_u64 v[32:33], v[32:33], 2, s[2:3]
	global_load_dword v59, v[32:33], off nt
	v_or_b32_e32 v32, 26, v16
	v_lshl_add_u64 v[34:35], v[14:15], 0, v[34:35]
	v_ashrrev_i32_e32 v33, 31, v32
	global_load_dword v58, v[34:35], off nt
	v_lshlrev_b64 v[34:35], 14, v[32:33]
	v_lshl_add_u64 v[32:33], v[32:33], 2, s[2:3]
	global_load_dword v61, v[32:33], off nt
	v_or_b32_e32 v32, 28, v16
	v_lshl_add_u64 v[34:35], v[14:15], 0, v[34:35]
	v_ashrrev_i32_e32 v33, 31, v32
	global_load_dword v60, v[34:35], off nt
	v_lshlrev_b64 v[34:35], 14, v[32:33]
	v_lshl_add_u64 v[32:33], v[32:33], 2, s[2:3]
	global_load_dword v63, v[32:33], off nt
	v_or_b32_e32 v32, 30, v16
	v_lshl_add_u64 v[34:35], v[14:15], 0, v[34:35]
	v_ashrrev_i32_e32 v33, 31, v32
	global_load_dword v62, v[34:35], off nt
	v_lshlrev_b64 v[34:35], 14, v[32:33]
	v_lshl_add_u64 v[32:33], v[32:33], 2, s[2:3]
	global_load_dword v65, v[32:33], off nt
	v_or_b32_e32 v32, 32, v16
	v_lshl_add_u64 v[34:35], v[14:15], 0, v[34:35]
	v_ashrrev_i32_e32 v33, 31, v32
	global_load_dword v64, v[34:35], off nt
	v_lshlrev_b64 v[34:35], 14, v[32:33]
	v_lshl_add_u64 v[32:33], v[32:33], 2, s[2:3]
	global_load_dword v67, v[32:33], off nt
	v_or_b32_e32 v32, 34, v16
	v_lshl_add_u64 v[34:35], v[14:15], 0, v[34:35]
	v_ashrrev_i32_e32 v33, 31, v32
	global_load_dword v66, v[34:35], off nt
	v_lshlrev_b64 v[34:35], 14, v[32:33]
	v_lshl_add_u64 v[32:33], v[32:33], 2, s[2:3]
	global_load_dword v69, v[32:33], off nt
	v_or_b32_e32 v32, 36, v16
	v_lshl_add_u64 v[34:35], v[14:15], 0, v[34:35]
	v_ashrrev_i32_e32 v33, 31, v32
	global_load_dword v68, v[34:35], off nt
	v_lshlrev_b64 v[34:35], 14, v[32:33]
	v_lshl_add_u64 v[32:33], v[32:33], 2, s[2:3]
	global_load_dword v71, v[32:33], off nt
	v_or_b32_e32 v32, 38, v16
	v_lshl_add_u64 v[34:35], v[14:15], 0, v[34:35]
	v_ashrrev_i32_e32 v33, 31, v32
	global_load_dword v70, v[34:35], off nt
	v_lshlrev_b64 v[34:35], 14, v[32:33]
	v_lshl_add_u64 v[32:33], v[32:33], 2, s[2:3]
	global_load_dword v73, v[32:33], off nt
	v_or_b32_e32 v32, 40, v16
	v_lshl_add_u64 v[34:35], v[14:15], 0, v[34:35]
	v_ashrrev_i32_e32 v33, 31, v32
	global_load_dword v72, v[34:35], off nt
	v_lshlrev_b64 v[34:35], 14, v[32:33]
	v_lshl_add_u64 v[32:33], v[32:33], 2, s[2:3]
	global_load_dword v75, v[32:33], off nt
	v_or_b32_e32 v32, 42, v16
	v_lshl_add_u64 v[34:35], v[14:15], 0, v[34:35]
	v_ashrrev_i32_e32 v33, 31, v32
	global_load_dword v74, v[34:35], off nt
	v_lshlrev_b64 v[34:35], 14, v[32:33]
	v_lshl_add_u64 v[32:33], v[32:33], 2, s[2:3]
	global_load_dword v77, v[32:33], off nt
	v_or_b32_e32 v32, 44, v16
	v_lshl_add_u64 v[34:35], v[14:15], 0, v[34:35]
	v_ashrrev_i32_e32 v33, 31, v32
	global_load_dword v76, v[34:35], off nt
	v_lshlrev_b64 v[34:35], 14, v[32:33]
	v_lshl_add_u64 v[32:33], v[32:33], 2, s[2:3]
	global_load_dword v79, v[32:33], off nt
	v_or_b32_e32 v32, 46, v16
	v_lshl_add_u64 v[34:35], v[14:15], 0, v[34:35]
	v_ashrrev_i32_e32 v33, 31, v32
	global_load_dword v78, v[34:35], off nt
	v_lshlrev_b64 v[34:35], 14, v[32:33]
	v_lshl_add_u64 v[32:33], v[32:33], 2, s[2:3]
	global_load_dword v81, v[32:33], off nt
	v_or_b32_e32 v32, 48, v16
	v_lshl_add_u64 v[34:35], v[14:15], 0, v[34:35]
	v_ashrrev_i32_e32 v33, 31, v32
	global_load_dword v80, v[34:35], off nt
	v_lshlrev_b64 v[34:35], 14, v[32:33]
	v_lshl_add_u64 v[32:33], v[32:33], 2, s[2:3]
	global_load_dword v83, v[32:33], off nt
	v_or_b32_e32 v32, 50, v16
	v_lshl_add_u64 v[34:35], v[14:15], 0, v[34:35]
	v_ashrrev_i32_e32 v33, 31, v32
	global_load_dword v82, v[34:35], off nt
	v_lshlrev_b64 v[34:35], 14, v[32:33]
	v_lshl_add_u64 v[32:33], v[32:33], 2, s[2:3]
	global_load_dword v85, v[32:33], off nt
	v_or_b32_e32 v32, 52, v16
	v_lshl_add_u64 v[34:35], v[14:15], 0, v[34:35]
	v_ashrrev_i32_e32 v33, 31, v32
	global_load_dword v84, v[34:35], off nt
	v_lshlrev_b64 v[34:35], 14, v[32:33]
	v_lshl_add_u64 v[32:33], v[32:33], 2, s[2:3]
	global_load_dword v87, v[32:33], off nt
	v_or_b32_e32 v32, 54, v16
	v_lshl_add_u64 v[34:35], v[14:15], 0, v[34:35]
	v_ashrrev_i32_e32 v33, 31, v32
	global_load_dword v86, v[34:35], off nt
	v_lshlrev_b64 v[34:35], 14, v[32:33]
	v_lshl_add_u64 v[32:33], v[32:33], 2, s[2:3]
	global_load_dword v89, v[32:33], off nt
	v_or_b32_e32 v32, 56, v16
	v_lshl_add_u64 v[34:35], v[14:15], 0, v[34:35]
	v_ashrrev_i32_e32 v33, 31, v32
	global_load_dword v88, v[34:35], off nt
	v_lshlrev_b64 v[34:35], 14, v[32:33]
	v_lshl_add_u64 v[32:33], v[32:33], 2, s[2:3]
	global_load_dword v91, v[32:33], off nt
	v_or_b32_e32 v32, 58, v16
	v_lshl_add_u64 v[34:35], v[14:15], 0, v[34:35]
	v_ashrrev_i32_e32 v33, 31, v32
	global_load_dword v90, v[34:35], off nt
	v_lshlrev_b64 v[34:35], 14, v[32:33]
	v_lshl_add_u64 v[32:33], v[32:33], 2, s[2:3]
	global_load_dword v93, v[32:33], off nt
	v_or_b32_e32 v32, 60, v16
	v_lshl_add_u64 v[34:35], v[14:15], 0, v[34:35]
	v_ashrrev_i32_e32 v33, 31, v32
	global_load_dword v92, v[34:35], off nt
	v_lshlrev_b64 v[34:35], 14, v[32:33]
	v_or_b32_e32 v16, 62, v16
	v_lshl_add_u64 v[34:35], v[14:15], 0, v[34:35]
	v_lshl_add_u64 v[32:33], v[32:33], 2, s[2:3]
	v_ashrrev_i32_e32 v17, 31, v16
	global_load_dword v34, v[34:35], off nt
	s_waitcnt vmcnt(59)
	v_mul_f32_e32 v0, v0, v31
	global_load_dword v35, v[32:33], off nt
	v_lshlrev_b64 v[32:33], 14, v[16:17]
	v_lshl_add_u64 v[14:15], v[14:15], 0, v[32:33]
	global_load_dword v32, v[14:15], off nt
	v_lshl_add_u64 v[14:15], v[16:17], 2, s[2:3]
	global_load_dword v14, v[14:15], off nt
	s_waitcnt vmcnt(60)
	v_mul_f32_e32 v15, v36, v37
	ds_write2_b32 v18, v0, v15 offset1:66
	s_waitcnt vmcnt(58)
	v_mul_f32_e32 v0, v38, v39
	s_waitcnt vmcnt(56)
	v_mul_f32_e32 v15, v40, v41
	ds_write2_b32 v18, v0, v15 offset0:132 offset1:198
	s_waitcnt vmcnt(54)
	v_mul_f32_e32 v0, v42, v43
	s_waitcnt vmcnt(52)
	v_mul_f32_e32 v15, v44, v45
	ds_write2_b32 v24, v0, v15 offset0:8 offset1:74
	s_waitcnt vmcnt(50)
	v_mul_f32_e32 v0, v46, v47
	s_waitcnt vmcnt(48)
	v_mul_f32_e32 v15, v48, v49
	ds_write2_b32 v24, v0, v15 offset0:140 offset1:206
	s_waitcnt vmcnt(46)
	v_mul_f32_e32 v0, v50, v51
	s_waitcnt vmcnt(44)
	v_mul_f32_e32 v15, v52, v53
	ds_write2_b32 v25, v0, v15 offset0:16 offset1:82
	s_waitcnt vmcnt(42)
	v_mul_f32_e32 v0, v54, v55
	s_waitcnt vmcnt(40)
	v_mul_f32_e32 v15, v56, v57
	ds_write2_b32 v25, v0, v15 offset0:148 offset1:214
	s_waitcnt vmcnt(38)
	v_mul_f32_e32 v0, v58, v59
	s_waitcnt vmcnt(36)
	v_mul_f32_e32 v15, v60, v61
	ds_write2_b32 v26, v0, v15 offset0:24 offset1:90
	s_waitcnt vmcnt(34)
	v_mul_f32_e32 v0, v62, v63
	s_waitcnt vmcnt(32)
	v_mul_f32_e32 v15, v64, v65
	ds_write2_b32 v26, v0, v15 offset0:156 offset1:222
	s_waitcnt vmcnt(30)
	v_mul_f32_e32 v0, v66, v67
	s_waitcnt vmcnt(28)
	v_mul_f32_e32 v15, v68, v69
	ds_write2_b32 v27, v0, v15 offset0:32 offset1:98
	s_waitcnt vmcnt(26)
	v_mul_f32_e32 v0, v70, v71
	s_waitcnt vmcnt(24)
	v_mul_f32_e32 v15, v72, v73
	ds_write2_b32 v27, v0, v15 offset0:164 offset1:230
	s_waitcnt vmcnt(22)
	v_mul_f32_e32 v0, v74, v75
	s_waitcnt vmcnt(20)
	v_mul_f32_e32 v15, v76, v77
	ds_write2_b32 v28, v0, v15 offset0:40 offset1:106
	s_waitcnt vmcnt(18)
	v_mul_f32_e32 v0, v78, v79
	s_waitcnt vmcnt(16)
	v_mul_f32_e32 v15, v80, v81
	ds_write2_b32 v28, v0, v15 offset0:172 offset1:238
	s_waitcnt vmcnt(14)
	v_mul_f32_e32 v0, v82, v83
	v_add_u32_e32 v50, s4, v19
	s_ashr_i32 s7, s6, 31
	s_waitcnt vmcnt(12)
	v_mul_f32_e32 v15, v84, v85
	ds_write2_b32 v29, v0, v15 offset0:48 offset1:114
	v_ashrrev_i32_e32 v51, 31, v50
	v_lshl_add_u64 v[48:49], s[6:7], 1, v[12:13]
	v_lshlrev_b64 v[52:53], 11, v[50:51]
	v_lshl_add_u64 v[52:53], v[48:49], 0, v[52:53]
	s_waitcnt vmcnt(10)
	v_mul_f32_e32 v0, v86, v87
	s_waitcnt vmcnt(8)
	v_mul_f32_e32 v15, v88, v89
	ds_write2_b32 v29, v0, v15 offset0:180 offset1:246
	s_waitcnt vmcnt(6)
	v_mul_f32_e32 v0, v90, v91
	s_waitcnt vmcnt(4)
	v_mul_f32_e32 v15, v92, v93
	ds_write2_b32 v30, v0, v15 offset0:56 offset1:122
	s_waitcnt vmcnt(2)
	v_mul_f32_e32 v0, v34, v35
	s_waitcnt vmcnt(0)
	v_mul_f32_e32 v14, v32, v14
	ds_write2_b32 v30, v0, v14 offset0:188 offset1:254
	s_waitcnt lgkmcnt(0)
	ds_read2_b32 v[32:33], v20 offset0:33 offset1:41
	ds_read2_b32 v[34:35], v20 offset1:8
	ds_read2_b32 v[36:37], v20 offset0:66 offset1:74
	ds_read2_b32 v[38:39], v20 offset0:99 offset1:107
	ds_read2_b32 v[40:41], v20 offset0:132 offset1:140
	ds_read2_b32 v[42:43], v20 offset0:165 offset1:173
	ds_read2_b32 v[44:45], v20 offset0:198 offset1:206
	ds_read2_b32 v[46:47], v20 offset0:231 offset1:239
	s_waitcnt lgkmcnt(6)
	v_cvt_pk_bf16_f32 v14, v34, v32
	s_waitcnt lgkmcnt(4)
	v_cvt_pk_bf16_f32 v15, v36, v38
	s_waitcnt lgkmcnt(2)
	v_cvt_pk_bf16_f32 v16, v40, v42
	v_add_u32_e32 v32, 8, v50
	s_waitcnt lgkmcnt(0)
	v_cvt_pk_bf16_f32 v17, v44, v46
	global_store_dwordx4 v[52:53], v[14:17], off
	s_nop 1
	v_cvt_pk_bf16_f32 v14, v35, v33
	v_ashrrev_i32_e32 v33, 31, v32
	v_cvt_pk_bf16_f32 v15, v37, v39
	v_cvt_pk_bf16_f32 v16, v41, v43
	v_cvt_pk_bf16_f32 v17, v45, v47
	v_lshlrev_b64 v[32:33], 11, v[32:33]
	ds_read2_b32 v[34:35], v20 offset0:49 offset1:57
	ds_read2_b32 v[36:37], v20 offset0:16 offset1:24
	ds_read2_b32 v[38:39], v20 offset0:82 offset1:90
	ds_read2_b32 v[40:41], v20 offset0:115 offset1:123
	ds_read2_b32 v[42:43], v20 offset0:148 offset1:156
	ds_read2_b32 v[44:45], v20 offset0:181 offset1:189
	ds_read2_b32 v[46:47], v20 offset0:214 offset1:222
	ds_read2_b32 v[52:53], v20 offset0:247 offset1:255
	v_lshl_add_u64 v[32:33], v[48:49], 0, v[32:33]
	global_store_dwordx4 v[32:33], v[14:17], off
	v_add_u32_e32 v32, 16, v50
	v_ashrrev_i32_e32 v33, 31, v32
	v_lshlrev_b64 v[32:33], 11, v[32:33]
	s_waitcnt lgkmcnt(6)
	v_cvt_pk_bf16_f32 v14, v36, v34
	s_waitcnt lgkmcnt(4)
	v_cvt_pk_bf16_f32 v15, v38, v40
	s_waitcnt lgkmcnt(2)
	v_cvt_pk_bf16_f32 v16, v42, v44
	s_waitcnt lgkmcnt(0)
	v_cvt_pk_bf16_f32 v17, v46, v52
	v_lshl_add_u64 v[32:33], v[48:49], 0, v[32:33]
	global_store_dwordx4 v[32:33], v[14:17], off
	v_add_u32_e32 v32, 24, v50
	v_ashrrev_i32_e32 v33, 31, v32
	v_lshlrev_b64 v[32:33], 11, v[32:33]
	v_cvt_pk_bf16_f32 v14, v37, v35
	v_cvt_pk_bf16_f32 v15, v39, v41
	v_cvt_pk_bf16_f32 v16, v43, v45
	v_cvt_pk_bf16_f32 v17, v47, v53
	v_lshl_add_u64 v[32:33], v[48:49], 0, v[32:33]
	global_store_dwordx4 v[32:33], v[14:17], off
	s_waitcnt lgkmcnt(0)
	s_branch .LBB0_848
